# all three GEMM k-loops and accumulator-to-image epilogues re-emitted for v_mfma_f32_16x16x32_bf16 (same bf16 MFMA kind, f32 accumulate), scalar m0/base LDS-DMA issue
# speedup vs baseline: 1.0213x; 1.0213x over previous
.LBB0_119:
	s_mul_hi_i32 s0, s24, 0x38e38e39
	s_lshr_b32 s1, s0, 31
	s_ashr_i32 s0, s0, 5
	s_add_i32 s0, s0, s1
	s_mul_i32 s1, s0, 0x90
	s_sub_i32 s1, s24, s1
	s_ashr_i32 s2, s1, 3
	s_add_i32 s3, s2, 15
	s_cmp_gt_i32 s2, 15
	s_cselect_b32 s47, s3, s2
	s_lshl_b32 s0, s0, 3
	s_add_i32 s0, s0, s45
	s_and_b32 s1, s1, 7
	s_or_b32 s0, s0, s1
	s_lshl_b32 s46, s47, 7
	s_lshl_b32 s48, s0, 8
	v_readfirstlane_b32 s49, v1
	s_add_i32 s57, s46, 0xffffff00
	s_cmp_lt_i32 s49, 3
	s_cselect_b64 s[0:1], -1, 0
	s_and_b64 s[2:3], s[0:1], exec
	s_mul_i32 s89, s49, 0x60
	s_cselect_b32 s2, s48, s57
	s_add_i32 s40, s2, s89
	s_and_b64 s[0:1], s[0:1], exec
	v_readlane_b32 s0, v254, 62
	v_readlane_b32 s1, v254, 63
	v_readlane_b32 s12, v255, 10
	v_readlane_b32 s13, v255, 11
	v_readlane_b32 s2, v255, 0
	v_readlane_b32 s3, v255, 1
	s_cselect_b32 s1, s13, s43
	s_cselect_b32 s0, s12, s42
	s_ashr_i32 s41, s40, 31
	s_lshl_b64 s[2:3], s[40:41], 11
	s_mul_i32 s20, s49, 6
	s_add_u32 s58, s0, s2
	s_addc_u32 s59, s1, s3
	s_or_b32 s38, s20, 1
	s_cmp_lt_i32 s38, 16
	s_cselect_b64 s[20:21], -1, 0
	s_lshl_b32 s41, s38, 4
	s_and_b64 s[38:39], s[20:21], exec
	s_cselect_b32 s44, s48, s57
	s_add_i32 s38, s44, s41
	s_and_b64 s[20:21], s[20:21], exec
	s_cselect_b32 s21, s13, s43
	s_cselect_b32 s20, s12, s42
	s_ashr_i32 s39, s38, 31
	s_lshl_b64 s[38:39], s[38:39], 11
	s_add_u32 s60, s20, s38
	s_addc_u32 s61, s21, s39
	s_add_i32 s38, s40, 32
	s_ashr_i32 s39, s38, 31
	s_lshl_b64 s[38:39], s[38:39], 11
	s_add_u32 s62, s0, s38
	s_addc_u32 s63, s1, s39
	s_add_i32 s40, s40, 48
	s_ashr_i32 s41, s40, 31
	s_lshl_b64 s[40:41], s[40:41], 11
	s_add_u32 s64, s0, s40
	s_addc_u32 s65, s1, s41
	s_cmp_lt_i32 s49, 2
	s_cselect_b64 s[40:41], -1, 0
	s_and_b64 s[66:67], s[40:41], exec
	s_cselect_b32 s49, s48, s57
	s_add_i32 s49, s89, s49
	s_add_i32 s66, s49, 64
	s_and_b64 s[40:41], s[40:41], exec
	s_cselect_b32 s41, s13, s43
	s_cselect_b32 s40, s12, s42
	s_ashr_i32 s67, s66, 31
	s_lshl_b64 s[66:67], s[66:67], 11
	s_add_u32 s68, s40, s66
	s_addc_u32 s69, s41, s67
	s_add_i32 vcc_lo, s49, 0x50
	s_ashr_i32 vcc_hi, vcc_lo, 31
	s_lshl_b64 vcc, vcc, 11
	s_add_u32 vcc_lo, s40, vcc_lo
	s_addc_u32 vcc_hi, s41, vcc_hi
	v_and_b32_e32 v188, 15, v160
	v_bfe_u32 v189, v160, 4, 2
	v_bfe_u32 v192, v188, 2, 2
	v_xor_b32_e32 v189, v189, v192
	v_lshlrev_b32_e32 v189, 4, v189
	v_lshrrev_b32_e32 v192, 6, v160
	v_lshrrev_b32_e32 v193, 1, v192
	v_and_b32_e32 v192, 1, v192
	v_lshl_add_u32 v193, v193, 7, v188
	v_lshl_add_u32 v192, v192, 6, v188
	v_lshl_add_u32 v216, v193, 6, v189
	v_lshl_add_u32 v217, v192, 6, v189
	v_add_u32_e32 v217, 0x4000, v217
	v_add_u32_e32 v218, 0x6000, v216
	v_add_u32_e32 v219, 0x6000, v217
	v_readfirstlane_b32 s49, v173
	v_add_u32_e32 v220, 64, v2
	s_mov_b32 s3, s49
	s_mov_b32 m0, s3
	s_add_u32 s3, s3, 0x400
	global_load_lds_dwordx4 v2, s[58:59]
	s_mov_b32 m0, s3
	s_add_u32 s3, s3, 0x400
	global_load_lds_dwordx4 v2, s[60:61]
	s_mov_b32 m0, s3
	s_add_u32 s3, s3, 0x400
	global_load_lds_dwordx4 v2, s[62:63]
	s_mov_b32 m0, s3
	s_add_u32 s3, s3, 0x400
	global_load_lds_dwordx4 v2, s[64:65]
	s_mov_b32 m0, s3
	s_add_u32 s3, s3, 0x400
	global_load_lds_dwordx4 v2, s[68:69]
	s_mov_b32 m0, s3
	s_nop 0
	global_load_lds_dwordx4 v2, vcc
	s_waitcnt vmcnt(0)
	s_barrier
	s_add_u32 s3, s49, 0x6000
	s_mov_b32 m0, s3
	s_add_u32 s3, s3, 0x400
	global_load_lds_dwordx4 v220, s[58:59]
	s_mov_b32 m0, s3
	s_add_u32 s3, s3, 0x400
	global_load_lds_dwordx4 v220, s[60:61]
	s_mov_b32 m0, s3
	s_add_u32 s3, s3, 0x400
	global_load_lds_dwordx4 v220, s[62:63]
	s_mov_b32 m0, s3
	s_add_u32 s3, s3, 0x400
	global_load_lds_dwordx4 v220, s[64:65]
	s_mov_b32 m0, s3
	s_add_u32 s3, s3, 0x400
	global_load_lds_dwordx4 v220, s[68:69]
	s_mov_b32 m0, s3
	s_nop 0
	global_load_lds_dwordx4 v220, vcc
	v_add_u32_e32 v220, 0x80, v2
	ds_read_b128 v[132:135], v217
	ds_read_b128 v[136:139], v217 offset:1024
	ds_read_b128 v[140:143], v217 offset:2048
	ds_read_b128 v[144:147], v217 offset:3072
	ds_read_b128 v[240:243], v216
	ds_read_b128 v[244:247], v216 offset:1024
	ds_read_b128 v[248:251], v216 offset:2048
	ds_read_b128 v[148:151], v216 offset:3072
	v_mov_b32_e32 v4, 0
	v_mov_b32_e32 v5, v4
	v_mov_b32_e32 v6, v4
	v_mov_b32_e32 v7, v4
	v_mov_b32_e32 v8, v4
	v_mov_b32_e32 v9, v4
	v_mov_b32_e32 v10, v4
	v_mov_b32_e32 v11, v4
	v_mov_b32_e32 v12, v4
	v_mov_b32_e32 v13, v4
	v_mov_b32_e32 v14, v4
	v_mov_b32_e32 v15, v4
	v_mov_b32_e32 v16, v4
	v_mov_b32_e32 v17, v4
	v_mov_b32_e32 v18, v4
	v_mov_b32_e32 v19, v4
	v_mov_b32_e32 v20, v4
	v_mov_b32_e32 v21, v4
	v_mov_b32_e32 v22, v4
	v_mov_b32_e32 v23, v4
	v_mov_b32_e32 v24, v4
	v_mov_b32_e32 v25, v4
	v_mov_b32_e32 v26, v4
	v_mov_b32_e32 v27, v4
	v_mov_b32_e32 v28, v4
	v_mov_b32_e32 v29, v4
	v_mov_b32_e32 v30, v4
	v_mov_b32_e32 v31, v4
	v_mov_b32_e32 v32, v4
	v_mov_b32_e32 v33, v4
	v_mov_b32_e32 v34, v4
	v_mov_b32_e32 v35, v4
	v_mov_b32_e32 v36, v4
	v_mov_b32_e32 v37, v4
	v_mov_b32_e32 v38, v4
	v_mov_b32_e32 v39, v4
	v_mov_b32_e32 v40, v4
	v_mov_b32_e32 v41, v4
	v_mov_b32_e32 v42, v4
	v_mov_b32_e32 v43, v4
	v_mov_b32_e32 v44, v4
	v_mov_b32_e32 v45, v4
	v_mov_b32_e32 v46, v4
	v_mov_b32_e32 v47, v4
	v_mov_b32_e32 v48, v4
	v_mov_b32_e32 v49, v4
	v_mov_b32_e32 v50, v4
	v_mov_b32_e32 v51, v4
	v_mov_b32_e32 v52, v4
	v_mov_b32_e32 v53, v4
	v_mov_b32_e32 v54, v4
	v_mov_b32_e32 v55, v4
	v_mov_b32_e32 v56, v4
	v_mov_b32_e32 v57, v4
	v_mov_b32_e32 v58, v4
	v_mov_b32_e32 v59, v4
	v_mov_b32_e32 v60, v4
	v_mov_b32_e32 v61, v4
	v_mov_b32_e32 v62, v4
	v_mov_b32_e32 v63, v4
	v_mov_b32_e32 v64, v4
	v_mov_b32_e32 v65, v4
	v_mov_b32_e32 v66, v4
	v_mov_b32_e32 v67, v4
	v_mov_b32_e32 v68, v4
	v_mov_b32_e32 v69, v4
	v_mov_b32_e32 v70, v4
	v_mov_b32_e32 v71, v4
	v_mov_b32_e32 v72, v4
	v_mov_b32_e32 v73, v4
	v_mov_b32_e32 v74, v4
	v_mov_b32_e32 v75, v4
	v_mov_b32_e32 v76, v4
	v_mov_b32_e32 v77, v4
	v_mov_b32_e32 v78, v4
	v_mov_b32_e32 v79, v4
	v_mov_b32_e32 v80, v4
	v_mov_b32_e32 v81, v4
	v_mov_b32_e32 v82, v4
	v_mov_b32_e32 v83, v4
	v_mov_b32_e32 v84, v4
	v_mov_b32_e32 v85, v4
	v_mov_b32_e32 v86, v4
	v_mov_b32_e32 v87, v4
	v_mov_b32_e32 v88, v4
	v_mov_b32_e32 v89, v4
	v_mov_b32_e32 v90, v4
	v_mov_b32_e32 v91, v4
	v_mov_b32_e32 v92, v4
	v_mov_b32_e32 v93, v4
	v_mov_b32_e32 v94, v4
	v_mov_b32_e32 v95, v4
	v_mov_b32_e32 v96, v4
	v_mov_b32_e32 v97, v4
	v_mov_b32_e32 v98, v4
	v_mov_b32_e32 v99, v4
	v_mov_b32_e32 v100, v4
	v_mov_b32_e32 v101, v4
	v_mov_b32_e32 v102, v4
	v_mov_b32_e32 v103, v4
	v_mov_b32_e32 v104, v4
	v_mov_b32_e32 v105, v4
	v_mov_b32_e32 v106, v4
	v_mov_b32_e32 v107, v4
	v_mov_b32_e32 v108, v4
	v_mov_b32_e32 v109, v4
	v_mov_b32_e32 v110, v4
	v_mov_b32_e32 v111, v4
	v_mov_b32_e32 v112, v4
	v_mov_b32_e32 v113, v4
	v_mov_b32_e32 v114, v4
	v_mov_b32_e32 v115, v4
	v_mov_b32_e32 v116, v4
	v_mov_b32_e32 v117, v4
	v_mov_b32_e32 v118, v4
	v_mov_b32_e32 v119, v4
	v_mov_b32_e32 v120, v4
	v_mov_b32_e32 v121, v4
	v_mov_b32_e32 v122, v4
	v_mov_b32_e32 v123, v4
	v_mov_b32_e32 v124, v4
	v_mov_b32_e32 v125, v4
	v_mov_b32_e32 v126, v4
	v_mov_b32_e32 v127, v4
	v_mov_b32_e32 v128, v4
	v_mov_b32_e32 v129, v4
	v_mov_b32_e32 v130, v4
	v_mov_b32_e32 v131, v4
	s_mov_b32 s0, 0
.Lg16_loop_gq:
	ds_read_b128 v[152:155], v216 offset:4096
	ds_read_b128 v[164:167], v216 offset:5120
	ds_read_b128 v[168:171], v216 offset:6144
	ds_read_b128 v[212:215], v216 offset:7168
	s_setprio 1
	s_waitcnt lgkmcnt(4)
	v_mfma_f32_16x16x32_bf16 v[100:103], v[132:135], v[240:243], v[100:103]
	v_mfma_f32_16x16x32_bf16 v[104:107], v[136:139], v[240:243], v[104:107]
	v_mfma_f32_16x16x32_bf16 v[108:111], v[140:143], v[240:243], v[108:111]
	v_mfma_f32_16x16x32_bf16 v[112:115], v[144:147], v[240:243], v[112:115]
	v_mfma_f32_16x16x32_bf16 v[116:119], v[132:135], v[244:247], v[116:119]
	v_mfma_f32_16x16x32_bf16 v[120:123], v[136:139], v[244:247], v[120:123]
	v_mfma_f32_16x16x32_bf16 v[124:127], v[140:143], v[244:247], v[124:127]
	v_mfma_f32_16x16x32_bf16 v[128:131], v[144:147], v[244:247], v[128:131]
	v_mfma_f32_16x16x32_bf16 v[68:71], v[132:135], v[248:251], v[68:71]
	v_mfma_f32_16x16x32_bf16 v[72:75], v[136:139], v[248:251], v[72:75]
	v_mfma_f32_16x16x32_bf16 v[76:79], v[140:143], v[248:251], v[76:79]
	v_mfma_f32_16x16x32_bf16 v[80:83], v[144:147], v[248:251], v[80:83]
	v_mfma_f32_16x16x32_bf16 v[84:87], v[132:135], v[148:151], v[84:87]
	v_mfma_f32_16x16x32_bf16 v[88:91], v[136:139], v[148:151], v[88:91]
	v_mfma_f32_16x16x32_bf16 v[92:95], v[140:143], v[148:151], v[92:95]
	v_mfma_f32_16x16x32_bf16 v[96:99], v[144:147], v[148:151], v[96:99]
	s_setprio 0
	s_waitcnt vmcnt(0) lgkmcnt(0)
	s_barrier
	s_cmp_lt_u32 s0, 15
	s_cbranch_scc0 .Lg16_nd0_gq
	s_mov_b32 s3, s49
	s_mov_b32 m0, s3
	s_add_u32 s3, s3, 0x400
	global_load_lds_dwordx4 v220, s[58:59]
	s_mov_b32 m0, s3
	s_add_u32 s3, s3, 0x400
	global_load_lds_dwordx4 v220, s[60:61]
	s_mov_b32 m0, s3
	s_add_u32 s3, s3, 0x400
	global_load_lds_dwordx4 v220, s[62:63]
	s_mov_b32 m0, s3
	s_add_u32 s3, s3, 0x400
	global_load_lds_dwordx4 v220, s[64:65]
	s_mov_b32 m0, s3
	s_add_u32 s3, s3, 0x400
	global_load_lds_dwordx4 v220, s[68:69]
	s_mov_b32 m0, s3
	s_nop 0
	global_load_lds_dwordx4 v220, vcc
	v_add_u32_e32 v220, 64, v220
.Lg16_nd0_gq:
	ds_read_b128 v[224:227], v219
	ds_read_b128 v[228:231], v219 offset:1024
	ds_read_b128 v[232:235], v219 offset:2048
	ds_read_b128 v[236:239], v219 offset:3072
	ds_read_b128 v[240:243], v218
	ds_read_b128 v[244:247], v218 offset:1024
	ds_read_b128 v[248:251], v218 offset:2048
	ds_read_b128 v[148:151], v218 offset:3072
	s_setprio 1
	v_mfma_f32_16x16x32_bf16 v[36:39], v[132:135], v[152:155], v[36:39]
	v_mfma_f32_16x16x32_bf16 v[40:43], v[136:139], v[152:155], v[40:43]
	v_mfma_f32_16x16x32_bf16 v[44:47], v[140:143], v[152:155], v[44:47]
	v_mfma_f32_16x16x32_bf16 v[48:51], v[144:147], v[152:155], v[48:51]
	v_mfma_f32_16x16x32_bf16 v[52:55], v[132:135], v[164:167], v[52:55]
	v_mfma_f32_16x16x32_bf16 v[56:59], v[136:139], v[164:167], v[56:59]
	v_mfma_f32_16x16x32_bf16 v[60:63], v[140:143], v[164:167], v[60:63]
	v_mfma_f32_16x16x32_bf16 v[64:67], v[144:147], v[164:167], v[64:67]
	v_mfma_f32_16x16x32_bf16 v[4:7], v[132:135], v[168:171], v[4:7]
	v_mfma_f32_16x16x32_bf16 v[8:11], v[136:139], v[168:171], v[8:11]
	v_mfma_f32_16x16x32_bf16 v[12:15], v[140:143], v[168:171], v[12:15]
	v_mfma_f32_16x16x32_bf16 v[16:19], v[144:147], v[168:171], v[16:19]
	v_mfma_f32_16x16x32_bf16 v[20:23], v[132:135], v[212:215], v[20:23]
	v_mfma_f32_16x16x32_bf16 v[24:27], v[136:139], v[212:215], v[24:27]
	v_mfma_f32_16x16x32_bf16 v[28:31], v[140:143], v[212:215], v[28:31]
	v_mfma_f32_16x16x32_bf16 v[32:35], v[144:147], v[212:215], v[32:35]
	s_setprio 0
	ds_read_b128 v[152:155], v218 offset:4096
	ds_read_b128 v[164:167], v218 offset:5120
	ds_read_b128 v[168:171], v218 offset:6144
	ds_read_b128 v[212:215], v218 offset:7168
	s_setprio 1
	s_waitcnt lgkmcnt(4)
	v_mfma_f32_16x16x32_bf16 v[100:103], v[224:227], v[240:243], v[100:103]
	v_mfma_f32_16x16x32_bf16 v[104:107], v[228:231], v[240:243], v[104:107]
	v_mfma_f32_16x16x32_bf16 v[108:111], v[232:235], v[240:243], v[108:111]
	v_mfma_f32_16x16x32_bf16 v[112:115], v[236:239], v[240:243], v[112:115]
	v_mfma_f32_16x16x32_bf16 v[116:119], v[224:227], v[244:247], v[116:119]
	v_mfma_f32_16x16x32_bf16 v[120:123], v[228:231], v[244:247], v[120:123]
	v_mfma_f32_16x16x32_bf16 v[124:127], v[232:235], v[244:247], v[124:127]
	v_mfma_f32_16x16x32_bf16 v[128:131], v[236:239], v[244:247], v[128:131]
	v_mfma_f32_16x16x32_bf16 v[68:71], v[224:227], v[248:251], v[68:71]
	v_mfma_f32_16x16x32_bf16 v[72:75], v[228:231], v[248:251], v[72:75]
	v_mfma_f32_16x16x32_bf16 v[76:79], v[232:235], v[248:251], v[76:79]
	v_mfma_f32_16x16x32_bf16 v[80:83], v[236:239], v[248:251], v[80:83]
	v_mfma_f32_16x16x32_bf16 v[84:87], v[224:227], v[148:151], v[84:87]
	v_mfma_f32_16x16x32_bf16 v[88:91], v[228:231], v[148:151], v[88:91]
	v_mfma_f32_16x16x32_bf16 v[92:95], v[232:235], v[148:151], v[92:95]
	v_mfma_f32_16x16x32_bf16 v[96:99], v[236:239], v[148:151], v[96:99]
	s_setprio 0
	s_waitcnt vmcnt(0) lgkmcnt(0)
	s_barrier
	s_cmp_lt_u32 s0, 15
	s_cbranch_scc0 .Lg16_nd1_gq
	s_add_u32 s3, s49, 0x6000
	s_mov_b32 m0, s3
	s_add_u32 s3, s3, 0x400
	global_load_lds_dwordx4 v220, s[58:59]
	s_mov_b32 m0, s3
	s_add_u32 s3, s3, 0x400
	global_load_lds_dwordx4 v220, s[60:61]
	s_mov_b32 m0, s3
	s_add_u32 s3, s3, 0x400
	global_load_lds_dwordx4 v220, s[62:63]
	s_mov_b32 m0, s3
	s_add_u32 s3, s3, 0x400
	global_load_lds_dwordx4 v220, s[64:65]
	s_mov_b32 m0, s3
	s_add_u32 s3, s3, 0x400
	global_load_lds_dwordx4 v220, s[68:69]
	s_mov_b32 m0, s3
	s_nop 0
	global_load_lds_dwordx4 v220, vcc
	v_add_u32_e32 v220, 64, v220
	ds_read_b128 v[132:135], v217
	ds_read_b128 v[136:139], v217 offset:1024
	ds_read_b128 v[140:143], v217 offset:2048
	ds_read_b128 v[144:147], v217 offset:3072
	ds_read_b128 v[240:243], v216
	ds_read_b128 v[244:247], v216 offset:1024
	ds_read_b128 v[248:251], v216 offset:2048
	ds_read_b128 v[148:151], v216 offset:3072
.Lg16_nd1_gq:
	s_setprio 1
	v_mfma_f32_16x16x32_bf16 v[36:39], v[224:227], v[152:155], v[36:39]
	v_mfma_f32_16x16x32_bf16 v[40:43], v[228:231], v[152:155], v[40:43]
	v_mfma_f32_16x16x32_bf16 v[44:47], v[232:235], v[152:155], v[44:47]
	v_mfma_f32_16x16x32_bf16 v[48:51], v[236:239], v[152:155], v[48:51]
	v_mfma_f32_16x16x32_bf16 v[52:55], v[224:227], v[164:167], v[52:55]
	v_mfma_f32_16x16x32_bf16 v[56:59], v[228:231], v[164:167], v[56:59]
	v_mfma_f32_16x16x32_bf16 v[60:63], v[232:235], v[164:167], v[60:63]
	v_mfma_f32_16x16x32_bf16 v[64:67], v[236:239], v[164:167], v[64:67]
	v_mfma_f32_16x16x32_bf16 v[4:7], v[224:227], v[168:171], v[4:7]
	v_mfma_f32_16x16x32_bf16 v[8:11], v[228:231], v[168:171], v[8:11]
	v_mfma_f32_16x16x32_bf16 v[12:15], v[232:235], v[168:171], v[12:15]
	v_mfma_f32_16x16x32_bf16 v[16:19], v[236:239], v[168:171], v[16:19]
	v_mfma_f32_16x16x32_bf16 v[20:23], v[224:227], v[212:215], v[20:23]
	v_mfma_f32_16x16x32_bf16 v[24:27], v[228:231], v[212:215], v[24:27]
	v_mfma_f32_16x16x32_bf16 v[28:31], v[232:235], v[212:215], v[28:31]
	v_mfma_f32_16x16x32_bf16 v[32:35], v[236:239], v[212:215], v[32:35]
	s_setprio 0
	s_add_u32 s0, s0, 1
	s_cmp_lt_u32 s0, 16
	s_cbranch_scc1 .Lg16_loop_gq
	s_nop 7
	s_and_b32 s0, s47, -4
	s_cmp_lg_u32 s0, 8
	s_cselect_b64 s[0:1], -1, 0
	s_add_i32 s2, s46, 0xfffffe00
	s_nop 5
	s_barrier
	s_cmp_lt_i32 s47, 8
	s_cselect_b32 s2, s46, s2
	v_or_b32_e32 v134, s2, v206
	v_and_b32_e32 v145, 63, v160
	v_lshrrev_b32_e32 v146, 6, v160
	v_and_b32_e32 v147, 15, v145
	v_lshrrev_b32_e32 v145, 4, v145
	v_mul_u32_u24_e32 v147, 0x90, v147
	v_lshl_add_u32 v147, v145, 3, v147
	v_mul_u32_u24_e32 v146, 0x2400, v146
	v_add_u32_e32 v144, v147, v146
	v_cvt_pk_bf16_f32 v136, v100, v101
	v_cvt_pk_bf16_f32 v137, v102, v103
	ds_write_b64 v144, v[136:137]
	v_cvt_pk_bf16_f32 v138, v104, v105
	v_cvt_pk_bf16_f32 v139, v106, v107
	ds_write_b64 v144, v[138:139] offset:32
	v_cvt_pk_bf16_f32 v140, v108, v109
	v_cvt_pk_bf16_f32 v141, v110, v111
	ds_write_b64 v144, v[140:141] offset:64
	v_cvt_pk_bf16_f32 v142, v112, v113
	v_cvt_pk_bf16_f32 v143, v114, v115
	ds_write_b64 v144, v[142:143] offset:96
	v_cvt_pk_bf16_f32 v136, v116, v117
	v_cvt_pk_bf16_f32 v137, v118, v119
	ds_write_b64 v144, v[136:137] offset:2304
	v_cvt_pk_bf16_f32 v138, v120, v121
	v_cvt_pk_bf16_f32 v139, v122, v123
	ds_write_b64 v144, v[138:139] offset:2336
	v_cvt_pk_bf16_f32 v140, v124, v125
	v_cvt_pk_bf16_f32 v141, v126, v127
	ds_write_b64 v144, v[140:141] offset:2368
	v_cvt_pk_bf16_f32 v142, v128, v129
	v_cvt_pk_bf16_f32 v143, v130, v131
	ds_write_b64 v144, v[142:143] offset:2400
	v_cvt_pk_bf16_f32 v136, v68, v69
	v_cvt_pk_bf16_f32 v137, v70, v71
	ds_write_b64 v144, v[136:137] offset:4608
	v_cvt_pk_bf16_f32 v138, v72, v73
	v_cvt_pk_bf16_f32 v139, v74, v75
	ds_write_b64 v144, v[138:139] offset:4640
	v_cvt_pk_bf16_f32 v140, v76, v77
	v_cvt_pk_bf16_f32 v141, v78, v79
	ds_write_b64 v144, v[140:141] offset:4672
	v_cvt_pk_bf16_f32 v142, v80, v81
	v_cvt_pk_bf16_f32 v143, v82, v83
	ds_write_b64 v144, v[142:143] offset:4704
	v_cvt_pk_bf16_f32 v136, v84, v85
	v_cvt_pk_bf16_f32 v137, v86, v87
	ds_write_b64 v144, v[136:137] offset:6912
	v_cvt_pk_bf16_f32 v138, v88, v89
	v_cvt_pk_bf16_f32 v139, v90, v91
	ds_write_b64 v144, v[138:139] offset:6944
	v_cvt_pk_bf16_f32 v140, v92, v93
	v_cvt_pk_bf16_f32 v141, v94, v95
	ds_write_b64 v144, v[140:141] offset:6976
	v_cvt_pk_bf16_f32 v142, v96, v97
	v_cvt_pk_bf16_f32 v143, v98, v99
	ds_write_b64 v144, v[142:143] offset:7008
	s_waitcnt lgkmcnt(0)
	v_ashrrev_i32_e32 v135, 31, v134
	v_add_u32_e32 v132, s48, v161
	s_mov_b64 s[2:3], -1
	s_and_b64 vcc, exec, s[0:1]
	v_lshlrev_b64 v[82:83], 1, v[134:135]
	s_cbranch_vccz .LBB0_123
	ds_read_b128 v[68:71], v210
	v_readlane_b32 s4, v254, 62
	v_readlane_b32 s18, v255, 12
	v_readlane_b32 s19, v255, 13
	v_or_b32_e32 v74, v132, v172
	v_readlane_b32 s5, v254, 63
	v_mov_b64_e32 v[72:73], s[18:19]
	v_mad_i64_i32 v[74:75], s[2:3], v74, s51, v[72:73]
	v_lshl_add_u64 v[74:75], v[74:75], 0, v[82:83]
	s_waitcnt lgkmcnt(0)
	global_store_dwordx4 v[74:75], v[68:71], off
	ds_read_b128 v[68:71], v210 offset:1152
	v_or_b32_e32 v74, v132, v176
	v_mad_i64_i32 v[74:75], s[2:3], v74, s51, v[72:73]
	v_lshl_add_u64 v[74:75], v[74:75], 0, v[82:83]
	s_waitcnt lgkmcnt(0)
	global_store_dwordx4 v[74:75], v[68:71], off
	ds_read_b128 v[68:71], v210 offset:2304
	v_or_b32_e32 v74, v132, v178
	v_mad_i64_i32 v[74:75], s[2:3], v74, s51, v[72:73]
	v_lshl_add_u64 v[74:75], v[74:75], 0, v[82:83]
	s_waitcnt lgkmcnt(0)
	global_store_dwordx4 v[74:75], v[68:71], off
	ds_read_b128 v[68:71], v210 offset:3456
	v_or_b32_e32 v74, v132, v179
	v_mad_i64_i32 v[74:75], s[2:3], v74, s51, v[72:73]
	v_lshl_add_u64 v[74:75], v[74:75], 0, v[82:83]
	s_waitcnt lgkmcnt(0)
	global_store_dwordx4 v[74:75], v[68:71], off
	ds_read_b128 v[68:71], v210 offset:4608
	v_or_b32_e32 v74, v132, v180
	v_mad_i64_i32 v[74:75], s[2:3], v74, s51, v[72:73]
	v_lshl_add_u64 v[74:75], v[74:75], 0, v[82:83]
	s_waitcnt lgkmcnt(0)
	global_store_dwordx4 v[74:75], v[68:71], off
	ds_read_b128 v[68:71], v210 offset:5760
	v_or_b32_e32 v74, v132, v181
	v_mad_i64_i32 v[74:75], s[2:3], v74, s51, v[72:73]
	v_lshl_add_u64 v[74:75], v[74:75], 0, v[82:83]
	s_waitcnt lgkmcnt(0)
	global_store_dwordx4 v[74:75], v[68:71], off
	ds_read_b128 v[68:71], v210 offset:6912
	v_or_b32_e32 v74, v132, v202
	v_mad_i64_i32 v[74:75], s[2:3], v74, s51, v[72:73]
	v_lshl_add_u64 v[74:75], v[74:75], 0, v[82:83]
	s_waitcnt lgkmcnt(0)
	global_store_dwordx4 v[74:75], v[68:71], off
	ds_read_b128 v[68:71], v210 offset:8064
	v_or_b32_e32 v74, v132, v203
	v_mad_i64_i32 v[72:73], s[2:3], v74, s51, v[72:73]
	v_lshl_add_u64 v[72:73], v[72:73], 0, v[82:83]
	s_mov_b64 s[2:3], 0
	v_readlane_b32 s6, v255, 0
	v_readlane_b32 s7, v255, 1
	v_readlane_b32 s8, v255, 2
	v_readlane_b32 s9, v255, 3
	v_readlane_b32 s10, v255, 4
	v_readlane_b32 s11, v255, 5
	v_readlane_b32 s12, v255, 6
	v_readlane_b32 s13, v255, 7
	v_readlane_b32 s14, v255, 8
	v_readlane_b32 s15, v255, 9
	v_readlane_b32 s16, v255, 10
	v_readlane_b32 s17, v255, 11
	s_waitcnt lgkmcnt(0)
	global_store_dwordx4 v[72:73], v[68:71], off

.LBB0_125:
	s_waitcnt lgkmcnt(0)
	v_and_b32_e32 v145, 63, v160
	v_lshrrev_b32_e32 v146, 6, v160
	v_and_b32_e32 v147, 15, v145
	v_lshrrev_b32_e32 v145, 4, v145
	v_mul_u32_u24_e32 v147, 0x90, v147
	v_lshl_add_u32 v147, v145, 3, v147
	v_mul_u32_u24_e32 v146, 0x2400, v146
	v_add_u32_e32 v144, v147, v146
	v_cvt_pk_bf16_f32 v136, v36, v37
	v_cvt_pk_bf16_f32 v137, v38, v39
	ds_write_b64 v144, v[136:137]
	v_cvt_pk_bf16_f32 v138, v40, v41
	v_cvt_pk_bf16_f32 v139, v42, v43
	ds_write_b64 v144, v[138:139] offset:32
	v_cvt_pk_bf16_f32 v140, v44, v45
	v_cvt_pk_bf16_f32 v141, v46, v47
	ds_write_b64 v144, v[140:141] offset:64
	v_cvt_pk_bf16_f32 v142, v48, v49
	v_cvt_pk_bf16_f32 v143, v50, v51
	ds_write_b64 v144, v[142:143] offset:96
	v_cvt_pk_bf16_f32 v136, v52, v53
	v_cvt_pk_bf16_f32 v137, v54, v55
	ds_write_b64 v144, v[136:137] offset:2304
	v_cvt_pk_bf16_f32 v138, v56, v57
	v_cvt_pk_bf16_f32 v139, v58, v59
	ds_write_b64 v144, v[138:139] offset:2336
	v_cvt_pk_bf16_f32 v140, v60, v61
	v_cvt_pk_bf16_f32 v141, v62, v63
	ds_write_b64 v144, v[140:141] offset:2368
	v_cvt_pk_bf16_f32 v142, v64, v65
	v_cvt_pk_bf16_f32 v143, v66, v67
	ds_write_b64 v144, v[142:143] offset:2400
	v_cvt_pk_bf16_f32 v136, v4, v5
	v_cvt_pk_bf16_f32 v137, v6, v7
	ds_write_b64 v144, v[136:137] offset:4608
	v_cvt_pk_bf16_f32 v138, v8, v9
	v_cvt_pk_bf16_f32 v139, v10, v11
	ds_write_b64 v144, v[138:139] offset:4640
	v_cvt_pk_bf16_f32 v140, v12, v13
	v_cvt_pk_bf16_f32 v141, v14, v15
	ds_write_b64 v144, v[140:141] offset:4672
	v_cvt_pk_bf16_f32 v142, v16, v17
	v_cvt_pk_bf16_f32 v143, v18, v19
	ds_write_b64 v144, v[142:143] offset:4704
	v_cvt_pk_bf16_f32 v136, v20, v21
	v_cvt_pk_bf16_f32 v137, v22, v23
	ds_write_b64 v144, v[136:137] offset:6912
	v_cvt_pk_bf16_f32 v138, v24, v25
	v_cvt_pk_bf16_f32 v139, v26, v27
	ds_write_b64 v144, v[138:139] offset:6944
	v_cvt_pk_bf16_f32 v140, v28, v29
	v_cvt_pk_bf16_f32 v141, v30, v31
	ds_write_b64 v144, v[140:141] offset:6976
	v_cvt_pk_bf16_f32 v142, v32, v33
	v_cvt_pk_bf16_f32 v143, v34, v35
	ds_write_b64 v144, v[142:143] offset:7008
	s_waitcnt lgkmcnt(0)
	v_or_b32_e32 v4, 64, v132
	s_andn2_b64 vcc, exec, s[0:1]
	s_mov_b64 s[0:1], -1
	s_cbranch_vccnz .LBB0_127
	ds_read_b128 v[6:9], v210
	v_readlane_b32 s0, v254, 62
	v_readlane_b32 s14, v255, 12
	v_readlane_b32 s15, v255, 13
	v_or_b32_e32 v5, v4, v172
	v_readlane_b32 s1, v254, 63
	v_mov_b64_e32 v[10:11], s[14:15]
	v_mad_i64_i32 v[12:13], s[0:1], v5, s51, v[10:11]
	v_lshl_add_u64 v[12:13], v[12:13], 0, v[82:83]
	s_waitcnt lgkmcnt(0)
	global_store_dwordx4 v[12:13], v[6:9], off
	ds_read_b128 v[6:9], v210 offset:1152
	v_or_b32_e32 v5, v4, v176
	v_mad_i64_i32 v[12:13], s[0:1], v5, s51, v[10:11]
	v_lshl_add_u64 v[12:13], v[12:13], 0, v[82:83]
	s_waitcnt lgkmcnt(0)
	global_store_dwordx4 v[12:13], v[6:9], off
	ds_read_b128 v[6:9], v210 offset:2304
	v_or_b32_e32 v5, v4, v178
	v_mad_i64_i32 v[12:13], s[0:1], v5, s51, v[10:11]
	v_lshl_add_u64 v[12:13], v[12:13], 0, v[82:83]
	s_waitcnt lgkmcnt(0)
	global_store_dwordx4 v[12:13], v[6:9], off
	ds_read_b128 v[6:9], v210 offset:3456
	v_or_b32_e32 v5, v4, v179
	v_mad_i64_i32 v[12:13], s[0:1], v5, s51, v[10:11]
	v_lshl_add_u64 v[12:13], v[12:13], 0, v[82:83]
	s_waitcnt lgkmcnt(0)
	global_store_dwordx4 v[12:13], v[6:9], off
	ds_read_b128 v[6:9], v210 offset:4608
	v_or_b32_e32 v5, v4, v180
	v_mad_i64_i32 v[12:13], s[0:1], v5, s51, v[10:11]
	v_lshl_add_u64 v[12:13], v[12:13], 0, v[82:83]
	s_waitcnt lgkmcnt(0)
	global_store_dwordx4 v[12:13], v[6:9], off
	ds_read_b128 v[6:9], v210 offset:5760
	v_or_b32_e32 v5, v4, v181
	v_mad_i64_i32 v[12:13], s[0:1], v5, s51, v[10:11]
	v_lshl_add_u64 v[12:13], v[12:13], 0, v[82:83]
	s_waitcnt lgkmcnt(0)
	global_store_dwordx4 v[12:13], v[6:9], off
	ds_read_b128 v[6:9], v210 offset:6912
	v_or_b32_e32 v5, v4, v202
	v_mad_i64_i32 v[12:13], s[0:1], v5, s51, v[10:11]
	v_lshl_add_u64 v[12:13], v[12:13], 0, v[82:83]
	s_waitcnt lgkmcnt(0)
	global_store_dwordx4 v[12:13], v[6:9], off
	ds_read_b128 v[6:9], v210 offset:8064
	v_or_b32_e32 v5, v4, v203
	v_mad_i64_i32 v[10:11], s[0:1], v5, s51, v[10:11]
	v_lshl_add_u64 v[10:11], v[10:11], 0, v[82:83]
	s_mov_b64 s[0:1], 0
	v_readlane_b32 s2, v255, 0
	v_readlane_b32 s3, v255, 1
	v_readlane_b32 s4, v255, 2
	v_readlane_b32 s5, v255, 3
	v_readlane_b32 s6, v255, 4
	v_readlane_b32 s7, v255, 5
	v_readlane_b32 s8, v255, 6
	v_readlane_b32 s9, v255, 7
	v_readlane_b32 s10, v255, 8
	v_readlane_b32 s11, v255, 9
	v_readlane_b32 s12, v255, 10
	v_readlane_b32 s13, v255, 11
	s_waitcnt lgkmcnt(0)
	global_store_dwordx4 v[10:11], v[6:9], off

.LBB0_240:
	s_mul_hi_i32 s0, s24, 0x88888889
	s_add_i32 s0, s0, s24
	s_lshr_b32 s1, s0, 31
	s_ashr_i32 s0, s0, 6
	s_add_i32 s0, s0, s1
	s_mul_i32 s1, s0, 0x78
	s_sub_i32 s1, s24, s1
	s_ashr_i32 s47, s1, 3
	s_lshl_b32 s0, s0, 3
	s_add_i32 s48, s47, 16
	s_add_i32 s0, s0, s45
	s_and_b32 s1, s1, 7
	s_or_b32 s0, s0, s1
	s_lshl_b32 s46, s48, 7
	s_lshl_b32 s49, s0, 8
	v_readfirstlane_b32 s66, v1
	s_add_i32 s68, s46, 0xffffff00
	s_cmp_lt_i32 s66, 3
	s_cselect_b64 s[0:1], -1, 0
	s_and_b64 s[2:3], s[0:1], exec
	s_mul_i32 s89, s66, 0x60
	s_cselect_b32 s2, s49, s68
	s_add_i32 s40, s2, s89
	s_and_b64 s[0:1], s[0:1], exec
	v_readlane_b32 s0, v254, 62
	v_readlane_b32 s1, v254, 63
	v_readlane_b32 s12, v255, 10
	v_readlane_b32 s13, v255, 11
	v_readlane_b32 s2, v255, 0
	v_readlane_b32 s3, v255, 1
	s_cselect_b32 s1, s13, s43
	s_cselect_b32 s0, s12, s42
	s_ashr_i32 s41, s40, 31
	s_lshl_b64 s[2:3], s[40:41], 11
	s_mul_i32 s20, s66, 6
	s_add_u32 s58, s0, s2
	s_addc_u32 s59, s1, s3
	s_or_b32 s38, s20, 1
	s_cmp_lt_i32 s38, 16
	s_cselect_b64 s[20:21], -1, 0
	s_lshl_b32 s41, s38, 4
	s_and_b64 s[38:39], s[20:21], exec
	s_cselect_b32 s57, s49, s68
	s_add_i32 s38, s57, s41
	s_and_b64 s[20:21], s[20:21], exec
	s_cselect_b32 s21, s13, s43
	s_cselect_b32 s20, s12, s42
	s_ashr_i32 s39, s38, 31
	s_lshl_b64 s[38:39], s[38:39], 11
	s_add_u32 s60, s20, s38
	s_addc_u32 s61, s21, s39
	s_add_i32 s38, s40, 32
	s_ashr_i32 s39, s38, 31
	s_lshl_b64 s[38:39], s[38:39], 11
	s_add_u32 s62, s0, s38
	s_addc_u32 s63, s1, s39
	s_add_i32 s40, s40, 48
	s_ashr_i32 s41, s40, 31
	s_lshl_b64 s[40:41], s[40:41], 11
	s_add_u32 s64, s0, s40
	s_addc_u32 s65, s1, s41
	s_cmp_lt_i32 s66, 2
	s_cselect_b64 s[40:41], -1, 0
	s_and_b64 s[66:67], s[40:41], exec
	s_cselect_b32 s66, s49, s68
	s_add_i32 vcc_lo, s89, s66
	s_add_i32 s66, vcc_lo, 64
	s_and_b64 s[40:41], s[40:41], exec
	s_cselect_b32 s41, s13, s43
	s_cselect_b32 s40, s12, s42
	s_ashr_i32 s67, s66, 31
	s_lshl_b64 s[66:67], s[66:67], 11
	s_add_u32 s68, s40, s66
	s_addc_u32 s69, s41, s67
	s_addk_i32 vcc_lo, 0x50
	s_ashr_i32 vcc_hi, vcc_lo, 31
	s_lshl_b64 vcc, vcc, 11
	s_add_u32 vcc_lo, s40, vcc_lo
	s_addc_u32 vcc_hi, s41, vcc_hi
	v_and_b32_e32 v188, 15, v160
	v_bfe_u32 v189, v160, 4, 2
	v_bfe_u32 v192, v188, 2, 2
	v_xor_b32_e32 v189, v189, v192
	v_lshlrev_b32_e32 v189, 4, v189
	v_lshrrev_b32_e32 v192, 6, v160
	v_lshrrev_b32_e32 v193, 1, v192
	v_and_b32_e32 v192, 1, v192
	v_lshl_add_u32 v193, v193, 7, v188
	v_lshl_add_u32 v192, v192, 6, v188
	v_lshl_add_u32 v216, v193, 6, v189
	v_lshl_add_u32 v217, v192, 6, v189
	v_add_u32_e32 v217, 0x4000, v217
	v_add_u32_e32 v218, 0x6000, v216
	v_add_u32_e32 v219, 0x6000, v217
	v_readfirstlane_b32 s44, v173
	v_add_u32_e32 v220, 64, v2
	s_mov_b32 s3, s44
	s_mov_b32 m0, s3
	s_add_u32 s3, s3, 0x400
	global_load_lds_dwordx4 v2, s[58:59]
	s_mov_b32 m0, s3
	s_add_u32 s3, s3, 0x400
	global_load_lds_dwordx4 v2, s[60:61]
	s_mov_b32 m0, s3
	s_add_u32 s3, s3, 0x400
	global_load_lds_dwordx4 v2, s[62:63]
	s_mov_b32 m0, s3
	s_add_u32 s3, s3, 0x400
	global_load_lds_dwordx4 v2, s[64:65]
	s_mov_b32 m0, s3
	s_add_u32 s3, s3, 0x400
	global_load_lds_dwordx4 v2, s[68:69]
	s_mov_b32 m0, s3
	s_nop 0
	global_load_lds_dwordx4 v2, vcc
	s_waitcnt vmcnt(0)
	s_barrier
	s_add_u32 s3, s44, 0x6000
	s_mov_b32 m0, s3
	s_add_u32 s3, s3, 0x400
	global_load_lds_dwordx4 v220, s[58:59]
	s_mov_b32 m0, s3
	s_add_u32 s3, s3, 0x400
	global_load_lds_dwordx4 v220, s[60:61]
	s_mov_b32 m0, s3
	s_add_u32 s3, s3, 0x400
	global_load_lds_dwordx4 v220, s[62:63]
	s_mov_b32 m0, s3
	s_add_u32 s3, s3, 0x400
	global_load_lds_dwordx4 v220, s[64:65]
	s_mov_b32 m0, s3
	s_add_u32 s3, s3, 0x400
	global_load_lds_dwordx4 v220, s[68:69]
	s_mov_b32 m0, s3
	s_nop 0
	global_load_lds_dwordx4 v220, vcc
	v_add_u32_e32 v220, 0x80, v2
	ds_read_b128 v[132:135], v217
	ds_read_b128 v[136:139], v217 offset:1024
	ds_read_b128 v[140:143], v217 offset:2048
	ds_read_b128 v[144:147], v217 offset:3072
	ds_read_b128 v[240:243], v216
	ds_read_b128 v[244:247], v216 offset:1024
	ds_read_b128 v[248:251], v216 offset:2048
	ds_read_b128 v[148:151], v216 offset:3072
	v_mov_b32_e32 v4, 0
	v_mov_b32_e32 v5, v4
	v_mov_b32_e32 v6, v4
	v_mov_b32_e32 v7, v4
	v_mov_b32_e32 v8, v4
	v_mov_b32_e32 v9, v4
	v_mov_b32_e32 v10, v4
	v_mov_b32_e32 v11, v4
	v_mov_b32_e32 v12, v4
	v_mov_b32_e32 v13, v4
	v_mov_b32_e32 v14, v4
	v_mov_b32_e32 v15, v4
	v_mov_b32_e32 v16, v4
	v_mov_b32_e32 v17, v4
	v_mov_b32_e32 v18, v4
	v_mov_b32_e32 v19, v4
	v_mov_b32_e32 v20, v4
	v_mov_b32_e32 v21, v4
	v_mov_b32_e32 v22, v4
	v_mov_b32_e32 v23, v4
	v_mov_b32_e32 v24, v4
	v_mov_b32_e32 v25, v4
	v_mov_b32_e32 v26, v4
	v_mov_b32_e32 v27, v4
	v_mov_b32_e32 v28, v4
	v_mov_b32_e32 v29, v4
	v_mov_b32_e32 v30, v4
	v_mov_b32_e32 v31, v4
	v_mov_b32_e32 v32, v4
	v_mov_b32_e32 v33, v4
	v_mov_b32_e32 v34, v4
	v_mov_b32_e32 v35, v4
	v_mov_b32_e32 v36, v4
	v_mov_b32_e32 v37, v4
	v_mov_b32_e32 v38, v4
	v_mov_b32_e32 v39, v4
	v_mov_b32_e32 v40, v4
	v_mov_b32_e32 v41, v4
	v_mov_b32_e32 v42, v4
	v_mov_b32_e32 v43, v4
	v_mov_b32_e32 v44, v4
	v_mov_b32_e32 v45, v4
	v_mov_b32_e32 v46, v4
	v_mov_b32_e32 v47, v4
	v_mov_b32_e32 v48, v4
	v_mov_b32_e32 v49, v4
	v_mov_b32_e32 v50, v4
	v_mov_b32_e32 v51, v4
	v_mov_b32_e32 v52, v4
	v_mov_b32_e32 v53, v4
	v_mov_b32_e32 v54, v4
	v_mov_b32_e32 v55, v4
	v_mov_b32_e32 v56, v4
	v_mov_b32_e32 v57, v4
	v_mov_b32_e32 v58, v4
	v_mov_b32_e32 v59, v4
	v_mov_b32_e32 v60, v4
	v_mov_b32_e32 v61, v4
	v_mov_b32_e32 v62, v4
	v_mov_b32_e32 v63, v4
	v_mov_b32_e32 v64, v4
	v_mov_b32_e32 v65, v4
	v_mov_b32_e32 v66, v4
	v_mov_b32_e32 v67, v4
	v_mov_b32_e32 v68, v4
	v_mov_b32_e32 v69, v4
	v_mov_b32_e32 v70, v4
	v_mov_b32_e32 v71, v4
	v_mov_b32_e32 v72, v4
	v_mov_b32_e32 v73, v4
	v_mov_b32_e32 v74, v4
	v_mov_b32_e32 v75, v4
	v_mov_b32_e32 v76, v4
	v_mov_b32_e32 v77, v4
	v_mov_b32_e32 v78, v4
	v_mov_b32_e32 v79, v4
	v_mov_b32_e32 v80, v4
	v_mov_b32_e32 v81, v4
	v_mov_b32_e32 v82, v4
	v_mov_b32_e32 v83, v4
	v_mov_b32_e32 v84, v4
	v_mov_b32_e32 v85, v4
	v_mov_b32_e32 v86, v4
	v_mov_b32_e32 v87, v4
	v_mov_b32_e32 v88, v4
	v_mov_b32_e32 v89, v4
	v_mov_b32_e32 v90, v4
	v_mov_b32_e32 v91, v4
	v_mov_b32_e32 v92, v4
	v_mov_b32_e32 v93, v4
	v_mov_b32_e32 v94, v4
	v_mov_b32_e32 v95, v4
	v_mov_b32_e32 v96, v4
	v_mov_b32_e32 v97, v4
	v_mov_b32_e32 v98, v4
	v_mov_b32_e32 v99, v4
	v_mov_b32_e32 v100, v4
	v_mov_b32_e32 v101, v4
	v_mov_b32_e32 v102, v4
	v_mov_b32_e32 v103, v4
	v_mov_b32_e32 v104, v4
	v_mov_b32_e32 v105, v4
	v_mov_b32_e32 v106, v4
	v_mov_b32_e32 v107, v4
	v_mov_b32_e32 v108, v4
	v_mov_b32_e32 v109, v4
	v_mov_b32_e32 v110, v4
	v_mov_b32_e32 v111, v4
	v_mov_b32_e32 v112, v4
	v_mov_b32_e32 v113, v4
	v_mov_b32_e32 v114, v4
	v_mov_b32_e32 v115, v4
	v_mov_b32_e32 v116, v4
	v_mov_b32_e32 v117, v4
	v_mov_b32_e32 v118, v4
	v_mov_b32_e32 v119, v4
	v_mov_b32_e32 v120, v4
	v_mov_b32_e32 v121, v4
	v_mov_b32_e32 v122, v4
	v_mov_b32_e32 v123, v4
	v_mov_b32_e32 v124, v4
	v_mov_b32_e32 v125, v4
	v_mov_b32_e32 v126, v4
	v_mov_b32_e32 v127, v4
	v_mov_b32_e32 v128, v4
	v_mov_b32_e32 v129, v4
	v_mov_b32_e32 v130, v4
	v_mov_b32_e32 v131, v4
	s_mov_b32 s0, 0
.Lg16_loop_g0a:
	ds_read_b128 v[152:155], v216 offset:4096
	ds_read_b128 v[164:167], v216 offset:5120
	ds_read_b128 v[168:171], v216 offset:6144
	ds_read_b128 v[212:215], v216 offset:7168
	s_setprio 1
	s_waitcnt lgkmcnt(4)
	v_mfma_f32_16x16x32_bf16 v[100:103], v[132:135], v[240:243], v[100:103]
	v_mfma_f32_16x16x32_bf16 v[104:107], v[136:139], v[240:243], v[104:107]
	v_mfma_f32_16x16x32_bf16 v[108:111], v[140:143], v[240:243], v[108:111]
	v_mfma_f32_16x16x32_bf16 v[112:115], v[144:147], v[240:243], v[112:115]
	v_mfma_f32_16x16x32_bf16 v[116:119], v[132:135], v[244:247], v[116:119]
	v_mfma_f32_16x16x32_bf16 v[120:123], v[136:139], v[244:247], v[120:123]
	v_mfma_f32_16x16x32_bf16 v[124:127], v[140:143], v[244:247], v[124:127]
	v_mfma_f32_16x16x32_bf16 v[128:131], v[144:147], v[244:247], v[128:131]
	v_mfma_f32_16x16x32_bf16 v[68:71], v[132:135], v[248:251], v[68:71]
	v_mfma_f32_16x16x32_bf16 v[72:75], v[136:139], v[248:251], v[72:75]
	v_mfma_f32_16x16x32_bf16 v[76:79], v[140:143], v[248:251], v[76:79]
	v_mfma_f32_16x16x32_bf16 v[80:83], v[144:147], v[248:251], v[80:83]
	v_mfma_f32_16x16x32_bf16 v[84:87], v[132:135], v[148:151], v[84:87]
	v_mfma_f32_16x16x32_bf16 v[88:91], v[136:139], v[148:151], v[88:91]
	v_mfma_f32_16x16x32_bf16 v[92:95], v[140:143], v[148:151], v[92:95]
	v_mfma_f32_16x16x32_bf16 v[96:99], v[144:147], v[148:151], v[96:99]
	s_setprio 0
	s_waitcnt vmcnt(0) lgkmcnt(0)
	s_barrier
	s_cmp_lt_u32 s0, 15
	s_cbranch_scc0 .Lg16_nd0_g0a
	s_mov_b32 s3, s44
	s_mov_b32 m0, s3
	s_add_u32 s3, s3, 0x400
	global_load_lds_dwordx4 v220, s[58:59]
	s_mov_b32 m0, s3
	s_add_u32 s3, s3, 0x400
	global_load_lds_dwordx4 v220, s[60:61]
	s_mov_b32 m0, s3
	s_add_u32 s3, s3, 0x400
	global_load_lds_dwordx4 v220, s[62:63]
	s_mov_b32 m0, s3
	s_add_u32 s3, s3, 0x400
	global_load_lds_dwordx4 v220, s[64:65]
	s_mov_b32 m0, s3
	s_add_u32 s3, s3, 0x400
	global_load_lds_dwordx4 v220, s[68:69]
	s_mov_b32 m0, s3
	s_nop 0
	global_load_lds_dwordx4 v220, vcc
	v_add_u32_e32 v220, 64, v220
.Lg16_nd0_g0a:
	ds_read_b128 v[224:227], v219
	ds_read_b128 v[228:231], v219 offset:1024
	ds_read_b128 v[232:235], v219 offset:2048
	ds_read_b128 v[236:239], v219 offset:3072
	ds_read_b128 v[240:243], v218
	ds_read_b128 v[244:247], v218 offset:1024
	ds_read_b128 v[248:251], v218 offset:2048
	ds_read_b128 v[148:151], v218 offset:3072
	s_setprio 1
	v_mfma_f32_16x16x32_bf16 v[36:39], v[132:135], v[152:155], v[36:39]
	v_mfma_f32_16x16x32_bf16 v[40:43], v[136:139], v[152:155], v[40:43]
	v_mfma_f32_16x16x32_bf16 v[44:47], v[140:143], v[152:155], v[44:47]
	v_mfma_f32_16x16x32_bf16 v[48:51], v[144:147], v[152:155], v[48:51]
	v_mfma_f32_16x16x32_bf16 v[52:55], v[132:135], v[164:167], v[52:55]
	v_mfma_f32_16x16x32_bf16 v[56:59], v[136:139], v[164:167], v[56:59]
	v_mfma_f32_16x16x32_bf16 v[60:63], v[140:143], v[164:167], v[60:63]
	v_mfma_f32_16x16x32_bf16 v[64:67], v[144:147], v[164:167], v[64:67]
	v_mfma_f32_16x16x32_bf16 v[4:7], v[132:135], v[168:171], v[4:7]
	v_mfma_f32_16x16x32_bf16 v[8:11], v[136:139], v[168:171], v[8:11]
	v_mfma_f32_16x16x32_bf16 v[12:15], v[140:143], v[168:171], v[12:15]
	v_mfma_f32_16x16x32_bf16 v[16:19], v[144:147], v[168:171], v[16:19]
	v_mfma_f32_16x16x32_bf16 v[20:23], v[132:135], v[212:215], v[20:23]
	v_mfma_f32_16x16x32_bf16 v[24:27], v[136:139], v[212:215], v[24:27]
	v_mfma_f32_16x16x32_bf16 v[28:31], v[140:143], v[212:215], v[28:31]
	v_mfma_f32_16x16x32_bf16 v[32:35], v[144:147], v[212:215], v[32:35]
	s_setprio 0
	ds_read_b128 v[152:155], v218 offset:4096
	ds_read_b128 v[164:167], v218 offset:5120
	ds_read_b128 v[168:171], v218 offset:6144
	ds_read_b128 v[212:215], v218 offset:7168
	s_setprio 1
	s_waitcnt lgkmcnt(4)
	v_mfma_f32_16x16x32_bf16 v[100:103], v[224:227], v[240:243], v[100:103]
	v_mfma_f32_16x16x32_bf16 v[104:107], v[228:231], v[240:243], v[104:107]
	v_mfma_f32_16x16x32_bf16 v[108:111], v[232:235], v[240:243], v[108:111]
	v_mfma_f32_16x16x32_bf16 v[112:115], v[236:239], v[240:243], v[112:115]
	v_mfma_f32_16x16x32_bf16 v[116:119], v[224:227], v[244:247], v[116:119]
	v_mfma_f32_16x16x32_bf16 v[120:123], v[228:231], v[244:247], v[120:123]
	v_mfma_f32_16x16x32_bf16 v[124:127], v[232:235], v[244:247], v[124:127]
	v_mfma_f32_16x16x32_bf16 v[128:131], v[236:239], v[244:247], v[128:131]
	v_mfma_f32_16x16x32_bf16 v[68:71], v[224:227], v[248:251], v[68:71]
	v_mfma_f32_16x16x32_bf16 v[72:75], v[228:231], v[248:251], v[72:75]
	v_mfma_f32_16x16x32_bf16 v[76:79], v[232:235], v[248:251], v[76:79]
	v_mfma_f32_16x16x32_bf16 v[80:83], v[236:239], v[248:251], v[80:83]
	v_mfma_f32_16x16x32_bf16 v[84:87], v[224:227], v[148:151], v[84:87]
	v_mfma_f32_16x16x32_bf16 v[88:91], v[228:231], v[148:151], v[88:91]
	v_mfma_f32_16x16x32_bf16 v[92:95], v[232:235], v[148:151], v[92:95]
	v_mfma_f32_16x16x32_bf16 v[96:99], v[236:239], v[148:151], v[96:99]
	s_setprio 0
	s_waitcnt vmcnt(0) lgkmcnt(0)
	s_barrier
	s_cmp_lt_u32 s0, 15
	s_cbranch_scc0 .Lg16_nd1_g0a
	s_add_u32 s3, s44, 0x6000
	s_mov_b32 m0, s3
	s_add_u32 s3, s3, 0x400
	global_load_lds_dwordx4 v220, s[58:59]
	s_mov_b32 m0, s3
	s_add_u32 s3, s3, 0x400
	global_load_lds_dwordx4 v220, s[60:61]
	s_mov_b32 m0, s3
	s_add_u32 s3, s3, 0x400
	global_load_lds_dwordx4 v220, s[62:63]
	s_mov_b32 m0, s3
	s_add_u32 s3, s3, 0x400
	global_load_lds_dwordx4 v220, s[64:65]
	s_mov_b32 m0, s3
	s_add_u32 s3, s3, 0x400
	global_load_lds_dwordx4 v220, s[68:69]
	s_mov_b32 m0, s3
	s_nop 0
	global_load_lds_dwordx4 v220, vcc
	v_add_u32_e32 v220, 64, v220
	ds_read_b128 v[132:135], v217
	ds_read_b128 v[136:139], v217 offset:1024
	ds_read_b128 v[140:143], v217 offset:2048
	ds_read_b128 v[144:147], v217 offset:3072
	ds_read_b128 v[240:243], v216
	ds_read_b128 v[244:247], v216 offset:1024
	ds_read_b128 v[248:251], v216 offset:2048
	ds_read_b128 v[148:151], v216 offset:3072
.Lg16_nd1_g0a:
	s_setprio 1
	v_mfma_f32_16x16x32_bf16 v[36:39], v[224:227], v[152:155], v[36:39]
	v_mfma_f32_16x16x32_bf16 v[40:43], v[228:231], v[152:155], v[40:43]
	v_mfma_f32_16x16x32_bf16 v[44:47], v[232:235], v[152:155], v[44:47]
	v_mfma_f32_16x16x32_bf16 v[48:51], v[236:239], v[152:155], v[48:51]
	v_mfma_f32_16x16x32_bf16 v[52:55], v[224:227], v[164:167], v[52:55]
	v_mfma_f32_16x16x32_bf16 v[56:59], v[228:231], v[164:167], v[56:59]
	v_mfma_f32_16x16x32_bf16 v[60:63], v[232:235], v[164:167], v[60:63]
	v_mfma_f32_16x16x32_bf16 v[64:67], v[236:239], v[164:167], v[64:67]
	v_mfma_f32_16x16x32_bf16 v[4:7], v[224:227], v[168:171], v[4:7]
	v_mfma_f32_16x16x32_bf16 v[8:11], v[228:231], v[168:171], v[8:11]
	v_mfma_f32_16x16x32_bf16 v[12:15], v[232:235], v[168:171], v[12:15]
	v_mfma_f32_16x16x32_bf16 v[16:19], v[236:239], v[168:171], v[16:19]
	v_mfma_f32_16x16x32_bf16 v[20:23], v[224:227], v[212:215], v[20:23]
	v_mfma_f32_16x16x32_bf16 v[24:27], v[228:231], v[212:215], v[24:27]
	v_mfma_f32_16x16x32_bf16 v[28:31], v[232:235], v[212:215], v[28:31]
	v_mfma_f32_16x16x32_bf16 v[32:35], v[236:239], v[212:215], v[32:35]
	s_setprio 0
	s_add_u32 s0, s0, 1
	s_cmp_lt_u32 s0, 16
	s_cbranch_scc1 .Lg16_loop_g0a
	s_nop 7
	s_and_b32 s0, s48, -4
	s_cmp_lg_u32 s0, 8
	s_cselect_b64 s[0:1], -1, 0
	s_add_i32 s2, s46, 0xfffffe00
	s_nop 5
	s_barrier
	s_cmp_lt_i32 s47, -8
	s_cselect_b32 s2, s46, s2
	v_or_b32_e32 v134, s2, v206
	v_and_b32_e32 v145, 63, v160
	v_lshrrev_b32_e32 v146, 6, v160
	v_and_b32_e32 v147, 15, v145
	v_lshrrev_b32_e32 v145, 4, v145
	v_mul_u32_u24_e32 v147, 0x90, v147
	v_lshl_add_u32 v147, v145, 3, v147
	v_mul_u32_u24_e32 v146, 0x2400, v146
	v_add_u32_e32 v144, v147, v146
	v_cvt_pk_bf16_f32 v136, v100, v101
	v_cvt_pk_bf16_f32 v137, v102, v103
	ds_write_b64 v144, v[136:137]
	v_cvt_pk_bf16_f32 v138, v104, v105
	v_cvt_pk_bf16_f32 v139, v106, v107
	ds_write_b64 v144, v[138:139] offset:32
	v_cvt_pk_bf16_f32 v140, v108, v109
	v_cvt_pk_bf16_f32 v141, v110, v111
	ds_write_b64 v144, v[140:141] offset:64
	v_cvt_pk_bf16_f32 v142, v112, v113
	v_cvt_pk_bf16_f32 v143, v114, v115
	ds_write_b64 v144, v[142:143] offset:96
	v_cvt_pk_bf16_f32 v136, v116, v117
	v_cvt_pk_bf16_f32 v137, v118, v119
	ds_write_b64 v144, v[136:137] offset:2304
	v_cvt_pk_bf16_f32 v138, v120, v121
	v_cvt_pk_bf16_f32 v139, v122, v123
	ds_write_b64 v144, v[138:139] offset:2336
	v_cvt_pk_bf16_f32 v140, v124, v125
	v_cvt_pk_bf16_f32 v141, v126, v127
	ds_write_b64 v144, v[140:141] offset:2368
	v_cvt_pk_bf16_f32 v142, v128, v129
	v_cvt_pk_bf16_f32 v143, v130, v131
	ds_write_b64 v144, v[142:143] offset:2400
	v_cvt_pk_bf16_f32 v136, v68, v69
	v_cvt_pk_bf16_f32 v137, v70, v71
	ds_write_b64 v144, v[136:137] offset:4608
	v_cvt_pk_bf16_f32 v138, v72, v73
	v_cvt_pk_bf16_f32 v139, v74, v75
	ds_write_b64 v144, v[138:139] offset:4640
	v_cvt_pk_bf16_f32 v140, v76, v77
	v_cvt_pk_bf16_f32 v141, v78, v79
	ds_write_b64 v144, v[140:141] offset:4672
	v_cvt_pk_bf16_f32 v142, v80, v81
	v_cvt_pk_bf16_f32 v143, v82, v83
	ds_write_b64 v144, v[142:143] offset:4704
	v_cvt_pk_bf16_f32 v136, v84, v85
	v_cvt_pk_bf16_f32 v137, v86, v87
	ds_write_b64 v144, v[136:137] offset:6912
	v_cvt_pk_bf16_f32 v138, v88, v89
	v_cvt_pk_bf16_f32 v139, v90, v91
	ds_write_b64 v144, v[138:139] offset:6944
	v_cvt_pk_bf16_f32 v140, v92, v93
	v_cvt_pk_bf16_f32 v141, v94, v95
	ds_write_b64 v144, v[140:141] offset:6976
	v_cvt_pk_bf16_f32 v142, v96, v97
	v_cvt_pk_bf16_f32 v143, v98, v99
	ds_write_b64 v144, v[142:143] offset:7008
	s_waitcnt lgkmcnt(0)
	v_ashrrev_i32_e32 v135, 31, v134
	v_add_u32_e32 v132, s49, v161
	s_mov_b64 s[2:3], -1
	s_and_b64 vcc, exec, s[0:1]
	v_lshlrev_b64 v[82:83], 1, v[134:135]
	s_cbranch_vccz .LBB0_244
	ds_read_b128 v[68:71], v210
	v_readlane_b32 s4, v254, 62
	v_readlane_b32 s18, v255, 12
	v_readlane_b32 s19, v255, 13
	v_or_b32_e32 v74, v132, v172
	v_readlane_b32 s5, v254, 63
	v_mov_b64_e32 v[72:73], s[18:19]
	v_mad_i64_i32 v[74:75], s[2:3], v74, s51, v[72:73]
	v_lshl_add_u64 v[74:75], v[74:75], 0, v[82:83]
	s_waitcnt lgkmcnt(0)
	global_store_dwordx4 v[74:75], v[68:71], off
	ds_read_b128 v[68:71], v210 offset:1152
	v_or_b32_e32 v74, v132, v176
	v_mad_i64_i32 v[74:75], s[2:3], v74, s51, v[72:73]
	v_lshl_add_u64 v[74:75], v[74:75], 0, v[82:83]
	s_waitcnt lgkmcnt(0)
	global_store_dwordx4 v[74:75], v[68:71], off
	ds_read_b128 v[68:71], v210 offset:2304
	v_or_b32_e32 v74, v132, v178
	v_mad_i64_i32 v[74:75], s[2:3], v74, s51, v[72:73]
	v_lshl_add_u64 v[74:75], v[74:75], 0, v[82:83]
	s_waitcnt lgkmcnt(0)
	global_store_dwordx4 v[74:75], v[68:71], off
	ds_read_b128 v[68:71], v210 offset:3456
	v_or_b32_e32 v74, v132, v179
	v_mad_i64_i32 v[74:75], s[2:3], v74, s51, v[72:73]
	v_lshl_add_u64 v[74:75], v[74:75], 0, v[82:83]
	s_waitcnt lgkmcnt(0)
	global_store_dwordx4 v[74:75], v[68:71], off
	ds_read_b128 v[68:71], v210 offset:4608
	v_or_b32_e32 v74, v132, v180
	v_mad_i64_i32 v[74:75], s[2:3], v74, s51, v[72:73]
	v_lshl_add_u64 v[74:75], v[74:75], 0, v[82:83]
	s_waitcnt lgkmcnt(0)
	global_store_dwordx4 v[74:75], v[68:71], off
	ds_read_b128 v[68:71], v210 offset:5760
	v_or_b32_e32 v74, v132, v181
	v_mad_i64_i32 v[74:75], s[2:3], v74, s51, v[72:73]
	v_lshl_add_u64 v[74:75], v[74:75], 0, v[82:83]
	s_waitcnt lgkmcnt(0)
	global_store_dwordx4 v[74:75], v[68:71], off
	ds_read_b128 v[68:71], v210 offset:6912
	v_or_b32_e32 v74, v132, v202
	v_mad_i64_i32 v[74:75], s[2:3], v74, s51, v[72:73]
	v_lshl_add_u64 v[74:75], v[74:75], 0, v[82:83]
	s_waitcnt lgkmcnt(0)
	global_store_dwordx4 v[74:75], v[68:71], off
	ds_read_b128 v[68:71], v210 offset:8064
	v_or_b32_e32 v74, v132, v203
	v_mad_i64_i32 v[72:73], s[2:3], v74, s51, v[72:73]
	v_lshl_add_u64 v[72:73], v[72:73], 0, v[82:83]
	s_mov_b64 s[2:3], 0
	v_readlane_b32 s6, v255, 0
	v_readlane_b32 s7, v255, 1
	v_readlane_b32 s8, v255, 2
	v_readlane_b32 s9, v255, 3
	v_readlane_b32 s10, v255, 4
	v_readlane_b32 s11, v255, 5
	v_readlane_b32 s12, v255, 6
	v_readlane_b32 s13, v255, 7
	v_readlane_b32 s14, v255, 8
	v_readlane_b32 s15, v255, 9
	v_readlane_b32 s16, v255, 10
	v_readlane_b32 s17, v255, 11
	s_waitcnt lgkmcnt(0)
	global_store_dwordx4 v[72:73], v[68:71], off

.LBB0_257:
	s_ashr_i32 s2, s24, 31
	s_lshr_b32 s2, s2, 26
	s_add_i32 s2, s24, s2
	s_and_b32 s3, s2, 0xffffffc0
	s_lshr_b32 s2, s2, 3
	s_sub_i32 s3, s24, s3
	s_and_b32 s2, s2, 0x1ffffff8
	s_add_i32 s2, s2, s49
	s_and_b32 s20, s3, 7
	s_or_b32 s2, s2, s20
	s_lshl_b32 s39, s2, 8
	s_lshl_b32 s2, s3, 4
	s_and_b32 s38, s2, 0xffffff80
	v_readfirstlane_b32 s57, v1
	s_add_i32 s68, s38, 0xffffff00
	s_cmp_lt_i32 s57, 3
	s_cselect_b64 s[2:3], -1, 0
	s_and_b64 s[20:21], s[2:3], exec
	s_mul_i32 s89, s57, 0x60
	s_cselect_b32 s20, s39, s68
	s_add_i32 s44, s20, s89
	v_readlane_b32 s72, v254, 44
	s_and_b64 s[2:3], s[2:3], exec
	v_readlane_b32 s74, v254, 46
	v_readlane_b32 s75, v254, 47
	s_cselect_b32 s3, s75, s47
	s_cselect_b32 s2, s74, s46
	s_ashr_i32 s45, s44, 31
	s_lshl_b64 s[20:21], s[44:45], 11
	s_mul_i32 s40, s57, 6
	s_add_u32 s58, s2, s20
	s_addc_u32 s59, s3, s21
	s_or_b32 s42, s40, 1
	s_cmp_lt_i32 s42, 16
	s_cselect_b64 s[40:41], -1, 0
	s_lshl_b32 s45, s42, 4
	s_and_b64 s[42:43], s[40:41], exec
	s_cselect_b32 s30, s39, s68
	s_add_i32 s42, s30, s45
	s_and_b64 s[40:41], s[40:41], exec
	s_cselect_b32 s41, s75, s47
	s_cselect_b32 s40, s74, s46
	s_ashr_i32 s43, s42, 31
	s_lshl_b64 s[42:43], s[42:43], 11
	s_add_u32 s60, s40, s42
	s_addc_u32 s61, s41, s43
	s_add_i32 s42, s44, 32
	s_ashr_i32 s43, s42, 31
	s_lshl_b64 s[42:43], s[42:43], 11
	s_add_u32 s62, s2, s42
	s_addc_u32 s63, s3, s43
	s_add_i32 s44, s44, 48
	s_ashr_i32 s45, s44, 31
	s_lshl_b64 s[44:45], s[44:45], 11
	s_add_u32 s64, s2, s44
	s_addc_u32 s65, s3, s45
	s_cmp_lt_i32 s57, 2
	s_cselect_b64 s[44:45], -1, 0
	s_and_b64 s[66:67], s[44:45], exec
	s_cselect_b32 s31, s39, s68
	s_add_i32 s31, s89, s31
	s_add_i32 s66, s31, 64
	s_and_b64 s[44:45], s[44:45], exec
	s_cselect_b32 s45, s75, s47
	s_cselect_b32 s44, s74, s46
	s_ashr_i32 s67, s66, 31
	s_lshl_b64 s[66:67], s[66:67], 11
	s_add_u32 s68, s44, s66
	s_addc_u32 s69, s45, s67
	s_add_i32 vcc_lo, s31, 0x50
	s_ashr_i32 vcc_hi, vcc_lo, 31
	s_lshl_b64 vcc, vcc, 11
	s_add_u32 vcc_lo, s44, vcc_lo
	s_addc_u32 vcc_hi, s45, vcc_hi
	v_and_b32_e32 v188, 15, v160
	v_bfe_u32 v189, v160, 4, 2
	v_bfe_u32 v192, v188, 2, 2
	v_xor_b32_e32 v189, v189, v192
	v_lshlrev_b32_e32 v189, 4, v189
	v_lshrrev_b32_e32 v192, 6, v160
	v_lshrrev_b32_e32 v193, 1, v192
	v_and_b32_e32 v192, 1, v192
	v_lshl_add_u32 v193, v193, 7, v188
	v_lshl_add_u32 v192, v192, 6, v188
	v_lshl_add_u32 v216, v193, 6, v189
	v_lshl_add_u32 v217, v192, 6, v189
	v_add_u32_e32 v217, 0x4000, v217
	v_add_u32_e32 v218, 0x6000, v216
	v_add_u32_e32 v219, 0x6000, v217
	v_readfirstlane_b32 s31, v172
	v_add_u32_e32 v220, 64, v2
	s_mov_b32 s41, s31
	s_mov_b32 m0, s41
	s_add_u32 s41, s41, 0x400
	global_load_lds_dwordx4 v2, s[58:59]
	s_mov_b32 m0, s41
	s_add_u32 s41, s41, 0x400
	global_load_lds_dwordx4 v2, s[60:61]
	s_mov_b32 m0, s41
	s_add_u32 s41, s41, 0x400
	global_load_lds_dwordx4 v2, s[62:63]
	s_mov_b32 m0, s41
	s_add_u32 s41, s41, 0x400
	global_load_lds_dwordx4 v2, s[64:65]
	s_mov_b32 m0, s41
	s_add_u32 s41, s41, 0x400
	global_load_lds_dwordx4 v2, s[68:69]
	s_mov_b32 m0, s41
	s_nop 0
	global_load_lds_dwordx4 v2, vcc
	s_waitcnt vmcnt(0)
	s_barrier
	s_add_u32 s41, s31, 0x6000
	s_mov_b32 m0, s41
	s_add_u32 s41, s41, 0x400
	global_load_lds_dwordx4 v220, s[58:59]
	s_mov_b32 m0, s41
	s_add_u32 s41, s41, 0x400
	global_load_lds_dwordx4 v220, s[60:61]
	s_mov_b32 m0, s41
	s_add_u32 s41, s41, 0x400
	global_load_lds_dwordx4 v220, s[62:63]
	s_mov_b32 m0, s41
	s_add_u32 s41, s41, 0x400
	global_load_lds_dwordx4 v220, s[64:65]
	s_mov_b32 m0, s41
	s_add_u32 s41, s41, 0x400
	global_load_lds_dwordx4 v220, s[68:69]
	s_mov_b32 m0, s41
	s_nop 0
	global_load_lds_dwordx4 v220, vcc
	v_add_u32_e32 v220, 0x80, v2
	ds_read_b128 v[132:135], v217
	ds_read_b128 v[136:139], v217 offset:1024
	ds_read_b128 v[140:143], v217 offset:2048
	ds_read_b128 v[144:147], v217 offset:3072
	ds_read_b128 v[240:243], v216
	ds_read_b128 v[244:247], v216 offset:1024
	ds_read_b128 v[248:251], v216 offset:2048
	ds_read_b128 v[148:151], v216 offset:3072
	v_mov_b32_e32 v4, 0
	v_mov_b32_e32 v5, v4
	v_mov_b32_e32 v6, v4
	v_mov_b32_e32 v7, v4
	v_mov_b32_e32 v8, v4
	v_mov_b32_e32 v9, v4
	v_mov_b32_e32 v10, v4
	v_mov_b32_e32 v11, v4
	v_mov_b32_e32 v12, v4
	v_mov_b32_e32 v13, v4
	v_mov_b32_e32 v14, v4
	v_mov_b32_e32 v15, v4
	v_mov_b32_e32 v16, v4
	v_mov_b32_e32 v17, v4
	v_mov_b32_e32 v18, v4
	v_mov_b32_e32 v19, v4
	v_mov_b32_e32 v20, v4
	v_mov_b32_e32 v21, v4
	v_mov_b32_e32 v22, v4
	v_mov_b32_e32 v23, v4
	v_mov_b32_e32 v24, v4
	v_mov_b32_e32 v25, v4
	v_mov_b32_e32 v26, v4
	v_mov_b32_e32 v27, v4
	v_mov_b32_e32 v28, v4
	v_mov_b32_e32 v29, v4
	v_mov_b32_e32 v30, v4
	v_mov_b32_e32 v31, v4
	v_mov_b32_e32 v32, v4
	v_mov_b32_e32 v33, v4
	v_mov_b32_e32 v34, v4
	v_mov_b32_e32 v35, v4
	v_mov_b32_e32 v36, v4
	v_mov_b32_e32 v37, v4
	v_mov_b32_e32 v38, v4
	v_mov_b32_e32 v39, v4
	v_mov_b32_e32 v40, v4
	v_mov_b32_e32 v41, v4
	v_mov_b32_e32 v42, v4
	v_mov_b32_e32 v43, v4
	v_mov_b32_e32 v44, v4
	v_mov_b32_e32 v45, v4
	v_mov_b32_e32 v46, v4
	v_mov_b32_e32 v47, v4
	v_mov_b32_e32 v48, v4
	v_mov_b32_e32 v49, v4
	v_mov_b32_e32 v50, v4
	v_mov_b32_e32 v51, v4
	v_mov_b32_e32 v52, v4
	v_mov_b32_e32 v53, v4
	v_mov_b32_e32 v54, v4
	v_mov_b32_e32 v55, v4
	v_mov_b32_e32 v56, v4
	v_mov_b32_e32 v57, v4
	v_mov_b32_e32 v58, v4
	v_mov_b32_e32 v59, v4
	v_mov_b32_e32 v60, v4
	v_mov_b32_e32 v61, v4
	v_mov_b32_e32 v62, v4
	v_mov_b32_e32 v63, v4
	v_mov_b32_e32 v64, v4
	v_mov_b32_e32 v65, v4
	v_mov_b32_e32 v66, v4
	v_mov_b32_e32 v67, v4
	v_mov_b32_e32 v68, v4
	v_mov_b32_e32 v69, v4
	v_mov_b32_e32 v70, v4
	v_mov_b32_e32 v71, v4
	v_mov_b32_e32 v72, v4
	v_mov_b32_e32 v73, v4
	v_mov_b32_e32 v74, v4
	v_mov_b32_e32 v75, v4
	v_mov_b32_e32 v76, v4
	v_mov_b32_e32 v77, v4
	v_mov_b32_e32 v78, v4
	v_mov_b32_e32 v79, v4
	v_mov_b32_e32 v80, v4
	v_mov_b32_e32 v81, v4
	v_mov_b32_e32 v82, v4
	v_mov_b32_e32 v83, v4
	v_mov_b32_e32 v84, v4
	v_mov_b32_e32 v85, v4
	v_mov_b32_e32 v86, v4
	v_mov_b32_e32 v87, v4
	v_mov_b32_e32 v88, v4
	v_mov_b32_e32 v89, v4
	v_mov_b32_e32 v90, v4
	v_mov_b32_e32 v91, v4
	v_mov_b32_e32 v92, v4
	v_mov_b32_e32 v93, v4
	v_mov_b32_e32 v94, v4
	v_mov_b32_e32 v95, v4
	v_mov_b32_e32 v96, v4
	v_mov_b32_e32 v97, v4
	v_mov_b32_e32 v98, v4
	v_mov_b32_e32 v99, v4
	v_mov_b32_e32 v100, v4
	v_mov_b32_e32 v101, v4
	v_mov_b32_e32 v102, v4
	v_mov_b32_e32 v103, v4
	v_mov_b32_e32 v104, v4
	v_mov_b32_e32 v105, v4
	v_mov_b32_e32 v106, v4
	v_mov_b32_e32 v107, v4
	v_mov_b32_e32 v108, v4
	v_mov_b32_e32 v109, v4
	v_mov_b32_e32 v110, v4
	v_mov_b32_e32 v111, v4
	v_mov_b32_e32 v112, v4
	v_mov_b32_e32 v113, v4
	v_mov_b32_e32 v114, v4
	v_mov_b32_e32 v115, v4
	v_mov_b32_e32 v116, v4
	v_mov_b32_e32 v117, v4
	v_mov_b32_e32 v118, v4
	v_mov_b32_e32 v119, v4
	v_mov_b32_e32 v120, v4
	v_mov_b32_e32 v121, v4
	v_mov_b32_e32 v122, v4
	v_mov_b32_e32 v123, v4
	v_mov_b32_e32 v124, v4
	v_mov_b32_e32 v125, v4
	v_mov_b32_e32 v126, v4
	v_mov_b32_e32 v127, v4
	v_mov_b32_e32 v128, v4
	v_mov_b32_e32 v129, v4
	v_mov_b32_e32 v130, v4
	v_mov_b32_e32 v131, v4
	s_mov_b32 s40, 0
.Lg16_loop_g1:
	ds_read_b128 v[152:155], v216 offset:4096
	ds_read_b128 v[164:167], v216 offset:5120
	ds_read_b128 v[168:171], v216 offset:6144
	ds_read_b128 v[212:215], v216 offset:7168
	s_setprio 1
	s_waitcnt lgkmcnt(4)
	v_mfma_f32_16x16x32_bf16 v[100:103], v[132:135], v[240:243], v[100:103]
	v_mfma_f32_16x16x32_bf16 v[104:107], v[136:139], v[240:243], v[104:107]
	v_mfma_f32_16x16x32_bf16 v[108:111], v[140:143], v[240:243], v[108:111]
	v_mfma_f32_16x16x32_bf16 v[112:115], v[144:147], v[240:243], v[112:115]
	v_mfma_f32_16x16x32_bf16 v[116:119], v[132:135], v[244:247], v[116:119]
	v_mfma_f32_16x16x32_bf16 v[120:123], v[136:139], v[244:247], v[120:123]
	v_mfma_f32_16x16x32_bf16 v[124:127], v[140:143], v[244:247], v[124:127]
	v_mfma_f32_16x16x32_bf16 v[128:131], v[144:147], v[244:247], v[128:131]
	v_mfma_f32_16x16x32_bf16 v[68:71], v[132:135], v[248:251], v[68:71]
	v_mfma_f32_16x16x32_bf16 v[72:75], v[136:139], v[248:251], v[72:75]
	v_mfma_f32_16x16x32_bf16 v[76:79], v[140:143], v[248:251], v[76:79]
	v_mfma_f32_16x16x32_bf16 v[80:83], v[144:147], v[248:251], v[80:83]
	v_mfma_f32_16x16x32_bf16 v[84:87], v[132:135], v[148:151], v[84:87]
	v_mfma_f32_16x16x32_bf16 v[88:91], v[136:139], v[148:151], v[88:91]
	v_mfma_f32_16x16x32_bf16 v[92:95], v[140:143], v[148:151], v[92:95]
	v_mfma_f32_16x16x32_bf16 v[96:99], v[144:147], v[148:151], v[96:99]
	s_setprio 0
	s_waitcnt vmcnt(0) lgkmcnt(0)
	s_barrier
	s_cmp_lt_u32 s40, 15
	s_cbranch_scc0 .Lg16_nd0_g1
	s_mov_b32 s41, s31
	s_mov_b32 m0, s41
	s_add_u32 s41, s41, 0x400
	global_load_lds_dwordx4 v220, s[58:59]
	s_mov_b32 m0, s41
	s_add_u32 s41, s41, 0x400
	global_load_lds_dwordx4 v220, s[60:61]
	s_mov_b32 m0, s41
	s_add_u32 s41, s41, 0x400
	global_load_lds_dwordx4 v220, s[62:63]
	s_mov_b32 m0, s41
	s_add_u32 s41, s41, 0x400
	global_load_lds_dwordx4 v220, s[64:65]
	s_mov_b32 m0, s41
	s_add_u32 s41, s41, 0x400
	global_load_lds_dwordx4 v220, s[68:69]
	s_mov_b32 m0, s41
	s_nop 0
	global_load_lds_dwordx4 v220, vcc
	v_add_u32_e32 v220, 64, v220
.Lg16_nd0_g1:
	ds_read_b128 v[224:227], v219
	ds_read_b128 v[228:231], v219 offset:1024
	ds_read_b128 v[232:235], v219 offset:2048
	ds_read_b128 v[236:239], v219 offset:3072
	ds_read_b128 v[240:243], v218
	ds_read_b128 v[244:247], v218 offset:1024
	ds_read_b128 v[248:251], v218 offset:2048
	ds_read_b128 v[148:151], v218 offset:3072
	s_setprio 1
	v_mfma_f32_16x16x32_bf16 v[36:39], v[132:135], v[152:155], v[36:39]
	v_mfma_f32_16x16x32_bf16 v[40:43], v[136:139], v[152:155], v[40:43]
	v_mfma_f32_16x16x32_bf16 v[44:47], v[140:143], v[152:155], v[44:47]
	v_mfma_f32_16x16x32_bf16 v[48:51], v[144:147], v[152:155], v[48:51]
	v_mfma_f32_16x16x32_bf16 v[52:55], v[132:135], v[164:167], v[52:55]
	v_mfma_f32_16x16x32_bf16 v[56:59], v[136:139], v[164:167], v[56:59]
	v_mfma_f32_16x16x32_bf16 v[60:63], v[140:143], v[164:167], v[60:63]
	v_mfma_f32_16x16x32_bf16 v[64:67], v[144:147], v[164:167], v[64:67]
	v_mfma_f32_16x16x32_bf16 v[4:7], v[132:135], v[168:171], v[4:7]
	v_mfma_f32_16x16x32_bf16 v[8:11], v[136:139], v[168:171], v[8:11]
	v_mfma_f32_16x16x32_bf16 v[12:15], v[140:143], v[168:171], v[12:15]
	v_mfma_f32_16x16x32_bf16 v[16:19], v[144:147], v[168:171], v[16:19]
	v_mfma_f32_16x16x32_bf16 v[20:23], v[132:135], v[212:215], v[20:23]
	v_mfma_f32_16x16x32_bf16 v[24:27], v[136:139], v[212:215], v[24:27]
	v_mfma_f32_16x16x32_bf16 v[28:31], v[140:143], v[212:215], v[28:31]
	v_mfma_f32_16x16x32_bf16 v[32:35], v[144:147], v[212:215], v[32:35]
	s_setprio 0
	ds_read_b128 v[152:155], v218 offset:4096
	ds_read_b128 v[164:167], v218 offset:5120
	ds_read_b128 v[168:171], v218 offset:6144
	ds_read_b128 v[212:215], v218 offset:7168
	s_setprio 1
	s_waitcnt lgkmcnt(4)
	v_mfma_f32_16x16x32_bf16 v[100:103], v[224:227], v[240:243], v[100:103]
	v_mfma_f32_16x16x32_bf16 v[104:107], v[228:231], v[240:243], v[104:107]
	v_mfma_f32_16x16x32_bf16 v[108:111], v[232:235], v[240:243], v[108:111]
	v_mfma_f32_16x16x32_bf16 v[112:115], v[236:239], v[240:243], v[112:115]
	v_mfma_f32_16x16x32_bf16 v[116:119], v[224:227], v[244:247], v[116:119]
	v_mfma_f32_16x16x32_bf16 v[120:123], v[228:231], v[244:247], v[120:123]
	v_mfma_f32_16x16x32_bf16 v[124:127], v[232:235], v[244:247], v[124:127]
	v_mfma_f32_16x16x32_bf16 v[128:131], v[236:239], v[244:247], v[128:131]
	v_mfma_f32_16x16x32_bf16 v[68:71], v[224:227], v[248:251], v[68:71]
	v_mfma_f32_16x16x32_bf16 v[72:75], v[228:231], v[248:251], v[72:75]
	v_mfma_f32_16x16x32_bf16 v[76:79], v[232:235], v[248:251], v[76:79]
	v_mfma_f32_16x16x32_bf16 v[80:83], v[236:239], v[248:251], v[80:83]
	v_mfma_f32_16x16x32_bf16 v[84:87], v[224:227], v[148:151], v[84:87]
	v_mfma_f32_16x16x32_bf16 v[88:91], v[228:231], v[148:151], v[88:91]
	v_mfma_f32_16x16x32_bf16 v[92:95], v[232:235], v[148:151], v[92:95]
	v_mfma_f32_16x16x32_bf16 v[96:99], v[236:239], v[148:151], v[96:99]
	s_setprio 0
	s_waitcnt vmcnt(0) lgkmcnt(0)
	s_barrier
	s_cmp_lt_u32 s40, 15
	s_cbranch_scc0 .Lg16_nd1_g1
	s_add_u32 s41, s31, 0x6000
	s_mov_b32 m0, s41
	s_add_u32 s41, s41, 0x400
	global_load_lds_dwordx4 v220, s[58:59]
	s_mov_b32 m0, s41
	s_add_u32 s41, s41, 0x400
	global_load_lds_dwordx4 v220, s[60:61]
	s_mov_b32 m0, s41
	s_add_u32 s41, s41, 0x400
	global_load_lds_dwordx4 v220, s[62:63]
	s_mov_b32 m0, s41
	s_add_u32 s41, s41, 0x400
	global_load_lds_dwordx4 v220, s[64:65]
	s_mov_b32 m0, s41
	s_add_u32 s41, s41, 0x400
	global_load_lds_dwordx4 v220, s[68:69]
	s_mov_b32 m0, s41
	s_nop 0
	global_load_lds_dwordx4 v220, vcc
	v_add_u32_e32 v220, 64, v220
	ds_read_b128 v[132:135], v217
	ds_read_b128 v[136:139], v217 offset:1024
	ds_read_b128 v[140:143], v217 offset:2048
	ds_read_b128 v[144:147], v217 offset:3072
	ds_read_b128 v[240:243], v216
	ds_read_b128 v[244:247], v216 offset:1024
	ds_read_b128 v[248:251], v216 offset:2048
	ds_read_b128 v[148:151], v216 offset:3072
.Lg16_nd1_g1:
	s_setprio 1
	v_mfma_f32_16x16x32_bf16 v[36:39], v[224:227], v[152:155], v[36:39]
	v_mfma_f32_16x16x32_bf16 v[40:43], v[228:231], v[152:155], v[40:43]
	v_mfma_f32_16x16x32_bf16 v[44:47], v[232:235], v[152:155], v[44:47]
	v_mfma_f32_16x16x32_bf16 v[48:51], v[236:239], v[152:155], v[48:51]
	v_mfma_f32_16x16x32_bf16 v[52:55], v[224:227], v[164:167], v[52:55]
	v_mfma_f32_16x16x32_bf16 v[56:59], v[228:231], v[164:167], v[56:59]
	v_mfma_f32_16x16x32_bf16 v[60:63], v[232:235], v[164:167], v[60:63]
	v_mfma_f32_16x16x32_bf16 v[64:67], v[236:239], v[164:167], v[64:67]
	v_mfma_f32_16x16x32_bf16 v[4:7], v[224:227], v[168:171], v[4:7]
	v_mfma_f32_16x16x32_bf16 v[8:11], v[228:231], v[168:171], v[8:11]
	v_mfma_f32_16x16x32_bf16 v[12:15], v[232:235], v[168:171], v[12:15]
	v_mfma_f32_16x16x32_bf16 v[16:19], v[236:239], v[168:171], v[16:19]
	v_mfma_f32_16x16x32_bf16 v[20:23], v[224:227], v[212:215], v[20:23]
	v_mfma_f32_16x16x32_bf16 v[24:27], v[228:231], v[212:215], v[24:27]
	v_mfma_f32_16x16x32_bf16 v[28:31], v[232:235], v[212:215], v[28:31]
	v_mfma_f32_16x16x32_bf16 v[32:35], v[236:239], v[212:215], v[32:35]
	s_setprio 0
	s_add_u32 s40, s40, 1
	s_cmp_lt_u32 s40, 16
	s_cbranch_scc1 .Lg16_loop_g1
	s_nop 7
	v_add_u32_e32 v132, s39, v161
	v_ashrrev_i32_e32 v133, 31, v132
	v_lshlrev_b64 v[132:133], 10, v[132:133]
	s_ashr_i32 s39, s38, 31
	v_lshl_add_u64 v[132:133], v[132:133], 0, s[38:39]
	v_or_b32_e32 v132, v132, v0
	v_lshlrev_b64 v[132:133], 2, v[132:133]
	s_barrier
	v_lshl_add_u64 v[154:155], s[0:1], 0, v[132:133]
	v_and_b32_e32 v217, 63, v160
	v_lshrrev_b32_e32 v218, 6, v160
	v_and_b32_e32 v219, 15, v217
	v_lshrrev_b32_e32 v217, 4, v217
	v_mul_u32_u24_e32 v219, 0x110, v219
	v_lshl_add_u32 v219, v217, 4, v219
	v_mul_u32_u24_e32 v218, 0x2200, v218
	v_add_u32_e32 v216, v219, v218
	ds_write_b128 v216, v[100:103]
	ds_write_b128 v216, v[104:107] offset:64
	ds_write_b128 v216, v[108:111] offset:128
	ds_write_b128 v216, v[112:115] offset:192
	ds_write_b128 v216, v[116:119] offset:4352
	ds_write_b128 v216, v[120:123] offset:4416
	ds_write_b128 v216, v[124:127] offset:4480
	ds_write_b128 v216, v[128:131] offset:4544
	global_load_dwordx4 v[164:167], v[154:155], off
	s_movk_i32 s2, 0x4000
	v_add_co_u32_e32 v100, vcc, s2, v154
	s_mov_b32 s57, 0x8000
	s_nop 0
	v_addc_co_u32_e32 v101, vcc, 0, v155, vcc
	global_load_dwordx4 v[168:171], v[100:101], off
	v_add_co_u32_e32 v100, vcc, s57, v154
	s_mov_b32 s3, 0xc000
	s_nop 0
	v_addc_co_u32_e32 v101, vcc, 0, v155, vcc
	global_load_dwordx4 v[202:205], v[100:101], off
	v_add_co_u32_e32 v100, vcc, s3, v154
	s_mov_b32 s20, 0x10000
	s_nop 0
	v_addc_co_u32_e32 v101, vcc, 0, v155, vcc
	global_load_dwordx4 v[148:151], v[100:101], off
	v_add_co_u32_e32 v100, vcc, s20, v154
	s_mov_b32 s21, 0x14000
	s_nop 0
	v_addc_co_u32_e32 v101, vcc, 0, v155, vcc
	global_load_dwordx4 v[144:147], v[100:101], off
	v_add_co_u32_e32 v100, vcc, s21, v154
	s_mov_b32 s30, 0x18000
	s_nop 0
	v_addc_co_u32_e32 v101, vcc, 0, v155, vcc
	global_load_dwordx4 v[140:143], v[100:101], off
	v_add_co_u32_e32 v100, vcc, s30, v154
	s_mov_b32 s31, 0x1c000
	s_nop 0
	v_addc_co_u32_e32 v101, vcc, 0, v155, vcc
	global_load_dwordx4 v[136:139], v[100:101], off
	v_readlane_b32 s4, v254, 62
	v_add_co_u32_e32 v100, vcc, s31, v154
	v_readlane_b32 s10, v255, 4
	v_readlane_b32 s11, v255, 5
	v_addc_co_u32_e32 v101, vcc, 0, v155, vcc
	s_nop 0
	v_lshl_add_u64 v[152:153], s[10:11], 0, v[132:133]
	global_load_dwordx4 v[132:135], v[100:101], off
	s_mov_b32 s38, 0x20000
	v_add_co_u32_e32 v100, vcc, s38, v154
	s_mov_b32 s39, 0x24000
	s_nop 0
	v_addc_co_u32_e32 v101, vcc, 0, v155, vcc
	global_load_dwordx4 v[128:131], v[100:101], off
	v_add_co_u32_e32 v100, vcc, s39, v154
	s_mov_b32 s40, 0x28000
	s_nop 0
	v_addc_co_u32_e32 v101, vcc, 0, v155, vcc
	global_load_dwordx4 v[124:127], v[100:101], off
	v_add_co_u32_e32 v100, vcc, s40, v154
	s_mov_b32 s41, 0x2c000
	s_nop 0
	v_addc_co_u32_e32 v101, vcc, 0, v155, vcc
	global_load_dwordx4 v[120:123], v[100:101], off
	v_add_co_u32_e32 v100, vcc, s41, v154
	s_mov_b32 s42, 0x30000
	s_nop 0
	v_addc_co_u32_e32 v101, vcc, 0, v155, vcc
	global_load_dwordx4 v[116:119], v[100:101], off
	v_add_co_u32_e32 v100, vcc, s42, v154
	s_mov_b32 s43, 0x34000
	s_nop 0
	v_addc_co_u32_e32 v101, vcc, 0, v155, vcc
	global_load_dwordx4 v[112:115], v[100:101], off
	v_add_co_u32_e32 v100, vcc, s43, v154
	s_mov_b32 s44, 0x38000
	s_nop 0
	v_addc_co_u32_e32 v101, vcc, 0, v155, vcc
	global_load_dwordx4 v[108:111], v[100:101], off
	v_add_co_u32_e32 v100, vcc, s44, v154
	s_mov_b32 s45, 0x3c000
	s_nop 0
	v_addc_co_u32_e32 v101, vcc, 0, v155, vcc
	global_load_dwordx4 v[104:107], v[100:101], off
	v_add_co_u32_e32 v100, vcc, s45, v154
	s_mov_b32 s58, 0x50000
	s_nop 0
	v_addc_co_u32_e32 v101, vcc, 0, v155, vcc
	global_load_dwordx4 v[100:103], v[100:101], off
	s_waitcnt lgkmcnt(0)
	ds_read_b128 v[206:209], v176
	s_mov_b32 s59, 0x58000
	s_mov_b32 s60, 0x5c000
	s_add_i32 s24, s24, s48
	s_cmpk_gt_i32 s24, 0x7f
	s_waitcnt vmcnt(15) lgkmcnt(0)
	v_pk_add_f32 v[164:165], v[164:165], v[206:207]
	v_pk_add_f32 v[166:167], v[166:167], v[208:209]
	global_store_dwordx4 v[152:153], v[164:167], off
	ds_read_b128 v[164:167], v176 offset:1088
	v_readlane_b32 s5, v254, 63
	v_readlane_b32 s6, v255, 0
	v_readlane_b32 s7, v255, 1
	v_readlane_b32 s8, v255, 2
	s_waitcnt vmcnt(15) lgkmcnt(0)
	v_pk_add_f32 v[164:165], v[168:169], v[164:165]
	v_add_co_u32_e32 v168, vcc, s2, v152
	v_pk_add_f32 v[166:167], v[170:171], v[166:167]
	s_nop 0
	v_addc_co_u32_e32 v169, vcc, 0, v153, vcc
	global_store_dwordx4 v[168:169], v[164:167], off
	ds_read_b128 v[164:167], v176 offset:2176
	v_add_co_u32_e32 v168, vcc, s57, v152
	s_mov_b32 s2, 0x7c000
	s_nop 0
	v_addc_co_u32_e32 v169, vcc, 0, v153, vcc
	s_waitcnt vmcnt(15) lgkmcnt(0)
	v_pk_add_f32 v[164:165], v[202:203], v[164:165]
	v_pk_add_f32 v[166:167], v[204:205], v[166:167]
	global_store_dwordx4 v[168:169], v[164:167], off
	ds_read_b128 v[164:167], v176 offset:3264
	v_readlane_b32 s9, v255, 3
	v_readlane_b32 s12, v255, 6
	v_readlane_b32 s13, v255, 7
	v_readlane_b32 s14, v255, 8
	s_waitcnt vmcnt(15) lgkmcnt(0)
	v_pk_add_f32 v[148:149], v[148:149], v[164:165]
	v_add_co_u32_e32 v164, vcc, s3, v152
	v_pk_add_f32 v[150:151], v[150:151], v[166:167]
	s_nop 0
	v_addc_co_u32_e32 v165, vcc, 0, v153, vcc
	global_store_dwordx4 v[164:165], v[148:151], off
	ds_read_b128 v[148:151], v176 offset:4352
	s_mov_b32 s3, 0x54000
	v_readlane_b32 s15, v255, 9
	v_readlane_b32 s16, v255, 10
	v_readlane_b32 s17, v255, 11
	s_waitcnt vmcnt(15) lgkmcnt(0)
	v_pk_add_f32 v[144:145], v[144:145], v[148:149]
	v_add_co_u32_e32 v148, vcc, s20, v152
	v_pk_add_f32 v[146:147], v[146:147], v[150:151]
	s_nop 0
	v_addc_co_u32_e32 v149, vcc, 0, v153, vcc
	global_store_dwordx4 v[148:149], v[144:147], off
	ds_read_b128 v[144:147], v176 offset:5440
	s_mov_b32 s20, 0x40000
	v_readlane_b32 s18, v255, 12
	v_readlane_b32 s19, v255, 13
	s_waitcnt vmcnt(15) lgkmcnt(0)
	v_pk_add_f32 v[140:141], v[140:141], v[144:145]
	v_add_co_u32_e32 v144, vcc, s21, v152
	v_pk_add_f32 v[142:143], v[142:143], v[146:147]
	s_nop 0
	v_addc_co_u32_e32 v145, vcc, 0, v153, vcc
	global_store_dwordx4 v[144:145], v[140:143], off
	ds_read_b128 v[140:143], v176 offset:6528
	s_mov_b32 s21, 0x44000
	s_waitcnt vmcnt(15) lgkmcnt(0)
	v_pk_add_f32 v[136:137], v[136:137], v[140:141]
	v_add_co_u32_e32 v140, vcc, s30, v152
	v_pk_add_f32 v[138:139], v[138:139], v[142:143]
	s_nop 0
	v_addc_co_u32_e32 v141, vcc, 0, v153, vcc
	global_store_dwordx4 v[140:141], v[136:139], off
	ds_read_b128 v[136:139], v176 offset:7616
	s_mov_b32 s30, 0x48000
	s_waitcnt vmcnt(15) lgkmcnt(0)
	v_pk_add_f32 v[132:133], v[132:133], v[136:137]
	v_add_co_u32_e32 v136, vcc, s31, v152
	v_pk_add_f32 v[134:135], v[134:135], v[138:139]
	s_nop 0
	v_addc_co_u32_e32 v137, vcc, 0, v153, vcc
	global_store_dwordx4 v[136:137], v[132:135], off
	s_waitcnt lgkmcnt(0)
	ds_write_b128 v216, v[68:71]
	ds_write_b128 v216, v[72:75] offset:64
	ds_write_b128 v216, v[76:79] offset:128
	ds_write_b128 v216, v[80:83] offset:192
	ds_write_b128 v216, v[84:87] offset:4352
	ds_write_b128 v216, v[88:91] offset:4416
	ds_write_b128 v216, v[92:95] offset:4480
	ds_write_b128 v216, v[96:99] offset:4544
	v_add_co_u32_e32 v68, vcc, s20, v154
	s_mov_b32 s31, 0x4c000
	s_nop 0
	v_addc_co_u32_e32 v69, vcc, 0, v155, vcc
	global_load_dwordx4 v[96:99], v[68:69], off
	v_add_co_u32_e32 v68, vcc, s21, v154
	s_nop 1
	v_addc_co_u32_e32 v69, vcc, 0, v155, vcc
	global_load_dwordx4 v[92:95], v[68:69], off
	v_add_co_u32_e32 v68, vcc, s30, v154
	s_nop 1
	v_addc_co_u32_e32 v69, vcc, 0, v155, vcc
	global_load_dwordx4 v[88:91], v[68:69], off
	v_add_co_u32_e32 v68, vcc, s31, v154
	s_nop 1
	v_addc_co_u32_e32 v69, vcc, 0, v155, vcc
	global_load_dwordx4 v[84:87], v[68:69], off
	v_add_co_u32_e32 v68, vcc, s58, v154
	s_nop 1
	v_addc_co_u32_e32 v69, vcc, 0, v155, vcc
	global_load_dwordx4 v[80:83], v[68:69], off
	v_add_co_u32_e32 v68, vcc, s3, v154
	s_nop 1
	v_addc_co_u32_e32 v69, vcc, 0, v155, vcc
	global_load_dwordx4 v[76:79], v[68:69], off
	v_add_co_u32_e32 v68, vcc, s59, v154
	s_nop 1
	v_addc_co_u32_e32 v69, vcc, 0, v155, vcc
	global_load_dwordx4 v[72:75], v[68:69], off
	v_add_co_u32_e32 v68, vcc, s60, v154
	s_nop 1
	v_addc_co_u32_e32 v69, vcc, 0, v155, vcc
	global_load_dwordx4 v[68:71], v[68:69], off
	s_waitcnt lgkmcnt(0)
	ds_read_b128 v[132:135], v176
	s_waitcnt vmcnt(23) lgkmcnt(0)
	v_pk_add_f32 v[128:129], v[128:129], v[132:133]
	v_add_co_u32_e32 v132, vcc, s38, v152
	v_pk_add_f32 v[130:131], v[130:131], v[134:135]
	s_nop 0
	v_addc_co_u32_e32 v133, vcc, 0, v153, vcc
	global_store_dwordx4 v[132:133], v[128:131], off
	ds_read_b128 v[128:131], v176 offset:1088
	s_mov_b32 s38, 0x60000
	s_waitcnt vmcnt(23) lgkmcnt(0)
	v_pk_add_f32 v[124:125], v[124:125], v[128:129]
	v_add_co_u32_e32 v128, vcc, s39, v152
	v_pk_add_f32 v[126:127], v[126:127], v[130:131]
	s_nop 0
	v_addc_co_u32_e32 v129, vcc, 0, v153, vcc
	global_store_dwordx4 v[128:129], v[124:127], off
	ds_read_b128 v[124:127], v176 offset:2176
	s_mov_b32 s39, 0x64000
	s_waitcnt vmcnt(23) lgkmcnt(0)
	v_pk_add_f32 v[120:121], v[120:121], v[124:125]
	v_add_co_u32_e32 v124, vcc, s40, v152
	v_pk_add_f32 v[122:123], v[122:123], v[126:127]
	s_nop 0
	v_addc_co_u32_e32 v125, vcc, 0, v153, vcc
	global_store_dwordx4 v[124:125], v[120:123], off
	ds_read_b128 v[120:123], v176 offset:3264
	s_mov_b32 s40, 0x68000
	s_waitcnt vmcnt(23) lgkmcnt(0)
	v_pk_add_f32 v[116:117], v[116:117], v[120:121]
	v_add_co_u32_e32 v120, vcc, s41, v152
	v_pk_add_f32 v[118:119], v[118:119], v[122:123]
	s_nop 0
	v_addc_co_u32_e32 v121, vcc, 0, v153, vcc
	global_store_dwordx4 v[120:121], v[116:119], off
	ds_read_b128 v[116:119], v176 offset:4352
	s_mov_b32 s41, 0x6c000
	s_waitcnt vmcnt(23) lgkmcnt(0)
	v_pk_add_f32 v[112:113], v[112:113], v[116:117]
	v_add_co_u32_e32 v116, vcc, s42, v152
	v_pk_add_f32 v[114:115], v[114:115], v[118:119]
	s_nop 0
	v_addc_co_u32_e32 v117, vcc, 0, v153, vcc
	global_store_dwordx4 v[116:117], v[112:115], off
	ds_read_b128 v[112:115], v176 offset:5440
	s_mov_b32 s42, 0x70000
	s_waitcnt vmcnt(23) lgkmcnt(0)
	v_pk_add_f32 v[108:109], v[108:109], v[112:113]
	v_add_co_u32_e32 v112, vcc, s43, v152
	v_pk_add_f32 v[110:111], v[110:111], v[114:115]
	s_nop 0
	v_addc_co_u32_e32 v113, vcc, 0, v153, vcc
	global_store_dwordx4 v[112:113], v[108:111], off
	ds_read_b128 v[108:111], v176 offset:6528
	s_mov_b32 s43, 0x74000
	s_waitcnt vmcnt(23) lgkmcnt(0)
	v_pk_add_f32 v[104:105], v[104:105], v[108:109]
	v_add_co_u32_e32 v108, vcc, s44, v152
	v_pk_add_f32 v[106:107], v[106:107], v[110:111]
	s_nop 0
	v_addc_co_u32_e32 v109, vcc, 0, v153, vcc
	global_store_dwordx4 v[108:109], v[104:107], off
	ds_read_b128 v[104:107], v176 offset:7616
	s_mov_b32 s44, 0x78000
	s_waitcnt vmcnt(23) lgkmcnt(0)
	v_pk_add_f32 v[100:101], v[100:101], v[104:105]
	v_add_co_u32_e32 v104, vcc, s45, v152
	v_pk_add_f32 v[102:103], v[102:103], v[106:107]
	s_nop 0
	v_addc_co_u32_e32 v105, vcc, 0, v153, vcc
	global_store_dwordx4 v[104:105], v[100:103], off
	s_waitcnt lgkmcnt(0)
	ds_write_b128 v216, v[36:39]
	ds_write_b128 v216, v[40:43] offset:64
	ds_write_b128 v216, v[44:47] offset:128
	ds_write_b128 v216, v[48:51] offset:192
	ds_write_b128 v216, v[52:55] offset:4352
	ds_write_b128 v216, v[56:59] offset:4416
	ds_write_b128 v216, v[60:63] offset:4480
	ds_write_b128 v216, v[64:67] offset:4544
	v_add_co_u32_e32 v36, vcc, s38, v154
	s_nop 1
	v_addc_co_u32_e32 v37, vcc, 0, v155, vcc
	global_load_dwordx4 v[64:67], v[36:37], off
	v_add_co_u32_e32 v36, vcc, s39, v154
	s_nop 1
	v_addc_co_u32_e32 v37, vcc, 0, v155, vcc
	global_load_dwordx4 v[60:63], v[36:37], off
	v_add_co_u32_e32 v36, vcc, s40, v154
	s_nop 1
	v_addc_co_u32_e32 v37, vcc, 0, v155, vcc
	global_load_dwordx4 v[56:59], v[36:37], off
	v_add_co_u32_e32 v36, vcc, s41, v154
	s_nop 1
	v_addc_co_u32_e32 v37, vcc, 0, v155, vcc
	global_load_dwordx4 v[52:55], v[36:37], off
	v_add_co_u32_e32 v36, vcc, s42, v154
	s_nop 1
	v_addc_co_u32_e32 v37, vcc, 0, v155, vcc
	global_load_dwordx4 v[48:51], v[36:37], off
	v_add_co_u32_e32 v36, vcc, s43, v154
	s_nop 1
	v_addc_co_u32_e32 v37, vcc, 0, v155, vcc
	global_load_dwordx4 v[44:47], v[36:37], off
	v_add_co_u32_e32 v36, vcc, s44, v154
	s_nop 1
	v_addc_co_u32_e32 v37, vcc, 0, v155, vcc
	global_load_dwordx4 v[40:43], v[36:37], off
	v_add_co_u32_e32 v36, vcc, s2, v154
	s_nop 1
	v_addc_co_u32_e32 v37, vcc, 0, v155, vcc
	global_load_dwordx4 v[36:39], v[36:37], off
	s_waitcnt lgkmcnt(0)
	ds_read_b128 v[100:103], v176
	s_waitcnt vmcnt(23) lgkmcnt(0)
	v_pk_add_f32 v[96:97], v[96:97], v[100:101]
	v_add_co_u32_e32 v100, vcc, s20, v152
	v_pk_add_f32 v[98:99], v[98:99], v[102:103]
	s_nop 0
	v_addc_co_u32_e32 v101, vcc, 0, v153, vcc
	global_store_dwordx4 v[100:101], v[96:99], off
	ds_read_b128 v[96:99], v176 offset:1088
	s_waitcnt vmcnt(23) lgkmcnt(0)
	v_pk_add_f32 v[92:93], v[92:93], v[96:97]
	v_add_co_u32_e32 v96, vcc, s21, v152
	v_pk_add_f32 v[94:95], v[94:95], v[98:99]
	s_nop 0
	v_addc_co_u32_e32 v97, vcc, 0, v153, vcc
	global_store_dwordx4 v[96:97], v[92:95], off
	ds_read_b128 v[92:95], v176 offset:2176
	s_waitcnt vmcnt(23) lgkmcnt(0)
	v_pk_add_f32 v[88:89], v[88:89], v[92:93]
	v_add_co_u32_e32 v92, vcc, s30, v152
	v_pk_add_f32 v[90:91], v[90:91], v[94:95]
	s_nop 0
	v_addc_co_u32_e32 v93, vcc, 0, v153, vcc
	global_store_dwordx4 v[92:93], v[88:91], off
	ds_read_b128 v[88:91], v176 offset:3264
	s_waitcnt vmcnt(23) lgkmcnt(0)
	v_pk_add_f32 v[84:85], v[84:85], v[88:89]
	v_add_co_u32_e32 v88, vcc, s31, v152
	v_pk_add_f32 v[86:87], v[86:87], v[90:91]
	s_nop 0
	v_addc_co_u32_e32 v89, vcc, 0, v153, vcc
	global_store_dwordx4 v[88:89], v[84:87], off
	ds_read_b128 v[84:87], v176 offset:4352
	s_waitcnt vmcnt(23) lgkmcnt(0)
	v_pk_add_f32 v[80:81], v[80:81], v[84:85]
	v_add_co_u32_e32 v84, vcc, s58, v152
	v_pk_add_f32 v[82:83], v[82:83], v[86:87]
	s_nop 0
	v_addc_co_u32_e32 v85, vcc, 0, v153, vcc
	global_store_dwordx4 v[84:85], v[80:83], off
	ds_read_b128 v[80:83], v176 offset:5440
	s_waitcnt vmcnt(23) lgkmcnt(0)
	v_pk_add_f32 v[76:77], v[76:77], v[80:81]
	v_add_co_u32_e32 v80, vcc, s3, v152
	v_pk_add_f32 v[78:79], v[78:79], v[82:83]
	s_nop 0
	v_addc_co_u32_e32 v81, vcc, 0, v153, vcc
	global_store_dwordx4 v[80:81], v[76:79], off
	ds_read_b128 v[76:79], v176 offset:6528
	s_waitcnt vmcnt(23) lgkmcnt(0)
	v_pk_add_f32 v[72:73], v[72:73], v[76:77]
	v_add_co_u32_e32 v76, vcc, s59, v152
	v_pk_add_f32 v[74:75], v[74:75], v[78:79]
	s_nop 0
	v_addc_co_u32_e32 v77, vcc, 0, v153, vcc
	global_store_dwordx4 v[76:77], v[72:75], off
	ds_read_b128 v[72:75], v176 offset:7616
	s_waitcnt vmcnt(23) lgkmcnt(0)
	v_pk_add_f32 v[68:69], v[68:69], v[72:73]
	v_add_co_u32_e32 v72, vcc, s60, v152
	v_pk_add_f32 v[70:71], v[70:71], v[74:75]
	s_nop 0
	v_addc_co_u32_e32 v73, vcc, 0, v153, vcc
	global_store_dwordx4 v[72:73], v[68:71], off
	s_waitcnt lgkmcnt(0)
	ds_write_b128 v216, v[4:7]
	ds_write_b128 v216, v[8:11] offset:64
	ds_write_b128 v216, v[12:15] offset:128
	ds_write_b128 v216, v[16:19] offset:192
	ds_write_b128 v216, v[20:23] offset:4352
	ds_write_b128 v216, v[24:27] offset:4416
	ds_write_b128 v216, v[28:31] offset:4480
	ds_write_b128 v216, v[32:35] offset:4544
	s_waitcnt lgkmcnt(0)
	ds_read_b128 v[4:7], v176
	v_add_co_u32_e32 v8, vcc, s38, v152
	s_waitcnt vmcnt(15) lgkmcnt(0)
	v_pk_add_f32 v[4:5], v[64:65], v[4:5]
	v_pk_add_f32 v[6:7], v[66:67], v[6:7]
	v_addc_co_u32_e32 v9, vcc, 0, v153, vcc
	global_store_dwordx4 v[8:9], v[4:7], off
	ds_read_b128 v[4:7], v176 offset:1088
	v_add_co_u32_e32 v8, vcc, s39, v152
	s_waitcnt vmcnt(15) lgkmcnt(0)
	v_pk_add_f32 v[4:5], v[60:61], v[4:5]
	v_pk_add_f32 v[6:7], v[62:63], v[6:7]
	v_addc_co_u32_e32 v9, vcc, 0, v153, vcc
	global_store_dwordx4 v[8:9], v[4:7], off
	ds_read_b128 v[4:7], v176 offset:2176
	v_add_co_u32_e32 v8, vcc, s40, v152
	s_waitcnt vmcnt(15) lgkmcnt(0)
	v_pk_add_f32 v[4:5], v[56:57], v[4:5]
	v_pk_add_f32 v[6:7], v[58:59], v[6:7]
	v_addc_co_u32_e32 v9, vcc, 0, v153, vcc
	global_store_dwordx4 v[8:9], v[4:7], off
	ds_read_b128 v[4:7], v176 offset:3264
	v_add_co_u32_e32 v8, vcc, s41, v152
	s_waitcnt vmcnt(15) lgkmcnt(0)
	v_pk_add_f32 v[4:5], v[52:53], v[4:5]
	v_pk_add_f32 v[6:7], v[54:55], v[6:7]
	v_addc_co_u32_e32 v9, vcc, 0, v153, vcc
	global_store_dwordx4 v[8:9], v[4:7], off
	ds_read_b128 v[4:7], v176 offset:4352
	v_add_co_u32_e32 v8, vcc, s42, v152
	s_waitcnt vmcnt(15) lgkmcnt(0)
	v_pk_add_f32 v[4:5], v[48:49], v[4:5]
	v_pk_add_f32 v[6:7], v[50:51], v[6:7]
	v_addc_co_u32_e32 v9, vcc, 0, v153, vcc
	global_store_dwordx4 v[8:9], v[4:7], off
	ds_read_b128 v[4:7], v176 offset:5440
	v_add_co_u32_e32 v8, vcc, s43, v152
	s_waitcnt vmcnt(15) lgkmcnt(0)
	v_pk_add_f32 v[4:5], v[44:45], v[4:5]
	v_pk_add_f32 v[6:7], v[46:47], v[6:7]
	v_addc_co_u32_e32 v9, vcc, 0, v153, vcc
	global_store_dwordx4 v[8:9], v[4:7], off
	ds_read_b128 v[4:7], v176 offset:6528
	v_add_co_u32_e32 v8, vcc, s44, v152
	s_waitcnt vmcnt(15) lgkmcnt(0)
	v_pk_add_f32 v[4:5], v[40:41], v[4:5]
	v_pk_add_f32 v[6:7], v[42:43], v[6:7]
	v_addc_co_u32_e32 v9, vcc, 0, v153, vcc
	global_store_dwordx4 v[8:9], v[4:7], off
	ds_read_b128 v[4:7], v176 offset:7616
	v_add_co_u32_e32 v8, vcc, 0x7c000, v152
	s_waitcnt vmcnt(15) lgkmcnt(0)
	v_pk_add_f32 v[4:5], v[36:37], v[4:5]
	v_pk_add_f32 v[6:7], v[38:39], v[6:7]
	v_addc_co_u32_e32 v9, vcc, 0, v153, vcc
	global_store_dwordx4 v[8:9], v[4:7], off
	s_barrier
	s_cbranch_scc0 .LBB0_257
